# speedup vs baseline: 1.0084x; 1.0084x over previous
; __device__ __forceinline__ void phase_inproj(const Params& p, char* smem) {
;     ...
; #pragma unroll
;     for (int m = 0; m < 8; ++m) {
;       const int row = mt * 256 + wr * 128 + m * 16 + fr;
; #pragma unroll
;       for (int n = 0; n < 4; ++n) {
;         const int c0 = wc * 64 + n * 16 + fq * 4;
;         f32x4 v = acc[m][n];
;         if (q8) {
;           const float rs = ((const float*)(ws + OFF_SXH))[row];
;           const float4 cw = *(const float4*)((const float*)(ws + OFF_SW8) + nt * 128 + c0);
;           v[0] *= rs * cw.x; v[1] *= rs * cw.y; v[2] *= rs * cw.z; v[3] *= rs * cw.w;
;         }
.LBB0_137:
	s_waitcnt vmcnt(11)
	v_lshl_add_u32 v128, s14, 8, v230
	s_lshl_b32 s12, s4, 7
	s_mov_b32 s13, 0
	v_or_b32_e32 v130, v128, v229
	s_lshl_b64 s[10:11], s[12:13], 2
	s_add_u32 s18, s69, s10
	v_ashrrev_i32_e32 v131, 31, v130
	s_addc_u32 s19, s70, s11
	s_waitcnt vmcnt(8)
	v_lshl_add_u64 v[136:137], v[130:131], 2, s[0:1]
	s_and_b64 vcc, exec, s[8:9]
	s_waitcnt vmcnt(4)
	v_lshlrev_b32_e32 v143, 2, v218
	s_cbranch_vccnz .LBB0_139
	global_load_dword v164, v[136:137], off
	global_load_dword v165, v[136:137], off offset:64
	global_load_dword v166, v[136:137], off offset:128
	global_load_dword v167, v[136:137], off offset:192
	global_load_dword v168, v[136:137], off offset:256
	global_load_dword v169, v[136:137], off offset:320
	global_load_dword v170, v[136:137], off offset:384
	global_load_dword v171, v[136:137], off offset:448
	global_load_dwordx4 v[148:151], v143, s[18:19]
	global_load_dwordx4 v[152:155], v143, s[18:19] offset:64
	global_load_dwordx4 v[156:159], v143, s[18:19] offset:128
	global_load_dwordx4 v[160:163], v143, s[18:19] offset:192
	s_waitcnt vmcnt(0)
	v_mov_b32_e32 v138, v164
	v_mov_b64_e32 v[132:133], v[148:149]
	v_mov_b64_e32 v[134:135], v[150:151]
	v_pk_mul_f32 v[134:135], v[138:139], v[134:135] op_sel_hi:[0,1]
	v_pk_mul_f32 v[132:133], v[138:139], v[132:133] op_sel_hi:[0,1]
	v_pk_mul_f32 v[124:125], v[124:125], v[132:133]
	v_pk_mul_f32 v[126:127], v[126:127], v[134:135]

; __device__ __forceinline__ void phase_inproj(const Params& p, char* smem) {
;     ...
;         if (q8) {
;           const float rs = ((const float*)(ws + OFF_SXH))[row];
;           const float4 cw = *(const float4*)((const float*)(ws + OFF_SW8) + nt * 128 + c0);
;           v[0] *= rs * cw.x; v[1] *= rs * cw.y; v[2] *= rs * cw.z; v[3] *= rs * cw.w;
;         }
.LBB0_157:
	s_and_b64 vcc, exec, s[8:9]
	s_cbranch_vccnz .LBB0_159
	v_mov_b32_e32 v144, v164
	v_mov_b64_e32 v[124:125], v[152:153]
	v_mov_b64_e32 v[126:127], v[154:155]
	v_pk_mul_f32 v[126:127], v[144:145], v[126:127] op_sel_hi:[0,1]
	v_pk_mul_f32 v[124:125], v[144:145], v[124:125] op_sel_hi:[0,1]
	v_pk_mul_f32 v[120:121], v[120:121], v[124:125]
	v_pk_mul_f32 v[122:123], v[122:123], v[126:127]

; __device__ __forceinline__ void phase_inproj(const Params& p, char* smem) {
;     ...
;         if (q8) {
;           const float rs = ((const float*)(ws + OFF_SXH))[row];
;           const float4 cw = *(const float4*)((const float*)(ws + OFF_SW8) + nt * 128 + c0);
;           v[0] *= rs * cw.x; v[1] *= rs * cw.y; v[2] *= rs * cw.z; v[3] *= rs * cw.w;
;         }
.LBB0_168:
	v_or_b32_e32 v120, 16, v130
	v_ashrrev_i32_e32 v121, 31, v120
	s_and_b64 vcc, exec, s[8:9]
	v_lshl_add_u64 v[118:119], v[120:121], 2, s[0:1]
	s_cbranch_vccnz .LBB0_170
	v_mov_b32_e32 v116, v165
	v_mov_b64_e32 v[112:113], v[148:149]
	v_mov_b64_e32 v[114:115], v[150:151]
	v_pk_mul_f32 v[114:115], v[116:117], v[114:115] op_sel_hi:[0,1]
	v_pk_mul_f32 v[112:113], v[116:117], v[112:113] op_sel_hi:[0,1]
	v_pk_mul_f32 v[108:109], v[108:109], v[112:113]
	v_pk_mul_f32 v[110:111], v[110:111], v[114:115]

; __device__ __forceinline__ void phase_inproj(const Params& p, char* smem) {
;     ...
;         if (q8) {
;           const float rs = ((const float*)(ws + OFF_SXH))[row];
;           const float4 cw = *(const float4*)((const float*)(ws + OFF_SW8) + nt * 128 + c0);
;           v[0] *= rs * cw.x; v[1] *= rs * cw.y; v[2] *= rs * cw.z; v[3] *= rs * cw.w;
;         }
.LBB0_182:
	v_or_b32_e32 v104, 32, v130
	v_ashrrev_i32_e32 v105, 31, v104
	s_and_b64 vcc, exec, s[8:9]
	v_lshl_add_u64 v[102:103], v[104:105], 2, s[0:1]
	s_cbranch_vccnz .LBB0_184
	v_mov_b32_e32 v100, v166
	v_mov_b64_e32 v[96:97], v[148:149]
	v_mov_b64_e32 v[98:99], v[150:151]
	v_pk_mul_f32 v[98:99], v[100:101], v[98:99] op_sel_hi:[0,1]
	v_pk_mul_f32 v[96:97], v[100:101], v[96:97] op_sel_hi:[0,1]
	v_pk_mul_f32 v[92:93], v[92:93], v[96:97]
	v_pk_mul_f32 v[94:95], v[94:95], v[98:99]

; __device__ __forceinline__ void phase_inproj(const Params& p, char* smem) {
;     ...
;         if (q8) {
;           const float rs = ((const float*)(ws + OFF_SXH))[row];
;           const float4 cw = *(const float4*)((const float*)(ws + OFF_SW8) + nt * 128 + c0);
;           v[0] *= rs * cw.x; v[1] *= rs * cw.y; v[2] *= rs * cw.z; v[3] *= rs * cw.w;
;         }
.LBB0_196:
	v_or_b32_e32 v88, 48, v130
	v_ashrrev_i32_e32 v89, 31, v88
	s_and_b64 vcc, exec, s[8:9]
	v_lshl_add_u64 v[86:87], v[88:89], 2, s[0:1]
	s_cbranch_vccnz .LBB0_198
	v_mov_b32_e32 v84, v167
	v_mov_b64_e32 v[80:81], v[148:149]
	v_mov_b64_e32 v[82:83], v[150:151]
	v_pk_mul_f32 v[82:83], v[84:85], v[82:83] op_sel_hi:[0,1]
	v_pk_mul_f32 v[80:81], v[84:85], v[80:81] op_sel_hi:[0,1]
	v_pk_mul_f32 v[76:77], v[76:77], v[80:81]
	v_pk_mul_f32 v[78:79], v[78:79], v[82:83]

; __device__ __forceinline__ void phase_inproj(const Params& p, char* smem) {
;     ...
;         if (q8) {
;           const float rs = ((const float*)(ws + OFF_SXH))[row];
;           const float4 cw = *(const float4*)((const float*)(ws + OFF_SW8) + nt * 128 + c0);
;           v[0] *= rs * cw.x; v[1] *= rs * cw.y; v[2] *= rs * cw.z; v[3] *= rs * cw.w;
;         }
.LBB0_210:
	v_or_b32_e32 v72, 64, v130
	v_ashrrev_i32_e32 v73, 31, v72
	s_and_b64 vcc, exec, s[8:9]
	v_lshl_add_u64 v[70:71], v[72:73], 2, s[0:1]
	s_cbranch_vccnz .LBB0_212
	v_mov_b32_e32 v68, v168
	v_mov_b64_e32 v[64:65], v[148:149]
	v_mov_b64_e32 v[66:67], v[150:151]
	v_pk_mul_f32 v[66:67], v[68:69], v[66:67] op_sel_hi:[0,1]
	v_pk_mul_f32 v[64:65], v[68:69], v[64:65] op_sel_hi:[0,1]
	v_pk_mul_f32 v[60:61], v[60:61], v[64:65]
	v_pk_mul_f32 v[62:63], v[62:63], v[66:67]

; __device__ __forceinline__ void phase_inproj(const Params& p, char* smem) {
;     ...
;         if (q8) {
;           const float rs = ((const float*)(ws + OFF_SXH))[row];
;           const float4 cw = *(const float4*)((const float*)(ws + OFF_SW8) + nt * 128 + c0);
;           v[0] *= rs * cw.x; v[1] *= rs * cw.y; v[2] *= rs * cw.z; v[3] *= rs * cw.w;
;         }
.LBB0_224:
	v_or_b32_e32 v56, 0x50, v130
	v_ashrrev_i32_e32 v57, 31, v56
	s_and_b64 vcc, exec, s[8:9]
	v_lshl_add_u64 v[54:55], v[56:57], 2, s[0:1]
	s_cbranch_vccnz .LBB0_226
	v_mov_b32_e32 v52, v169
	v_mov_b64_e32 v[48:49], v[148:149]
	v_mov_b64_e32 v[50:51], v[150:151]
	v_pk_mul_f32 v[50:51], v[52:53], v[50:51] op_sel_hi:[0,1]
	v_pk_mul_f32 v[48:49], v[52:53], v[48:49] op_sel_hi:[0,1]
	v_pk_mul_f32 v[44:45], v[44:45], v[48:49]
	v_pk_mul_f32 v[46:47], v[46:47], v[50:51]

; __device__ __forceinline__ void phase_inproj(const Params& p, char* smem) {
;     ...
;         if (q8) {
;           const float rs = ((const float*)(ws + OFF_SXH))[row];
;           const float4 cw = *(const float4*)((const float*)(ws + OFF_SW8) + nt * 128 + c0);
;           v[0] *= rs * cw.x; v[1] *= rs * cw.y; v[2] *= rs * cw.z; v[3] *= rs * cw.w;
;         }
.LBB0_238:
	v_or_b32_e32 v40, 0x60, v130
	v_ashrrev_i32_e32 v41, 31, v40
	s_and_b64 vcc, exec, s[8:9]
	v_lshl_add_u64 v[38:39], v[40:41], 2, s[0:1]
	s_cbranch_vccnz .LBB0_240
	v_mov_b32_e32 v36, v170
	v_mov_b64_e32 v[32:33], v[148:149]
	v_mov_b64_e32 v[34:35], v[150:151]
	v_pk_mul_f32 v[34:35], v[36:37], v[34:35] op_sel_hi:[0,1]
	v_pk_mul_f32 v[32:33], v[36:37], v[32:33] op_sel_hi:[0,1]
	v_pk_mul_f32 v[28:29], v[28:29], v[32:33]
	v_pk_mul_f32 v[30:31], v[30:31], v[34:35]

; __device__ __forceinline__ void phase_inproj(const Params& p, char* smem) {
;     ...
;         if (q8) {
;           const float rs = ((const float*)(ws + OFF_SXH))[row];
;           const float4 cw = *(const float4*)((const float*)(ws + OFF_SW8) + nt * 128 + c0);
;           v[0] *= rs * cw.x; v[1] *= rs * cw.y; v[2] *= rs * cw.z; v[3] *= rs * cw.w;
;         }
.LBB0_252:
	v_or_b32_e32 v24, 0x70, v130
	v_ashrrev_i32_e32 v25, 31, v24
	s_and_b64 vcc, exec, s[8:9]
	v_lshl_add_u64 v[22:23], v[24:25], 2, s[0:1]
	s_cbranch_vccnz .LBB0_254
	v_mov_b32_e32 v20, v171
	v_mov_b64_e32 v[16:17], v[148:149]
	v_mov_b64_e32 v[18:19], v[150:151]
	v_pk_mul_f32 v[18:19], v[20:21], v[18:19] op_sel_hi:[0,1]
	v_pk_mul_f32 v[16:17], v[20:21], v[16:17] op_sel_hi:[0,1]
	v_pk_mul_f32 v[12:13], v[12:13], v[16:17]
	v_pk_mul_f32 v[14:15], v[14:15], v[18:19]

; __device__ __forceinline__ void phase_inproj(const Params& p, char* smem) {
;     ...
;         if (q8) {
;           const float rs = ((const float*)(ws + OFF_SXH))[row];
;           const float4 cw = *(const float4*)((const float*)(ws + OFF_SW8) + nt * 128 + c0);
;           v[0] *= rs * cw.x; v[1] *= rs * cw.y; v[2] *= rs * cw.z; v[3] *= rs * cw.w;
;         }
.LBB0_277:
	v_mov_b32_e32 v124, v164
	v_mov_b64_e32 v[120:121], v[156:157]
	v_mov_b64_e32 v[122:123], v[158:159]
	v_pk_mul_f32 v[122:123], v[124:125], v[122:123] op_sel_hi:[0,1]
	v_pk_mul_f32 v[120:121], v[124:125], v[120:121] op_sel_hi:[0,1]
	v_pk_mul_f32 v[116:117], v[116:117], v[120:121]
	v_pk_mul_f32 v[118:119], v[118:119], v[122:123]
	s_and_b64 vcc, exec, s[12:13]
	s_mov_b64 s[58:59], -1
	s_cbranch_vccnz .LBB0_163

; __device__ __forceinline__ void phase_inproj(const Params& p, char* smem) {
;     ...
;         if (q8) {
;           const float rs = ((const float*)(ws + OFF_SXH))[row];
;           const float4 cw = *(const float4*)((const float*)(ws + OFF_SW8) + nt * 128 + c0);
;           v[0] *= rs * cw.x; v[1] *= rs * cw.y; v[2] *= rs * cw.z; v[3] *= rs * cw.w;
;         }
.LBB0_290:
	v_mov_b32_e32 v120, v164
	v_mov_b64_e32 v[116:117], v[160:161]
	v_mov_b64_e32 v[118:119], v[162:163]
	v_pk_mul_f32 v[118:119], v[120:121], v[118:119] op_sel_hi:[0,1]
	v_pk_mul_f32 v[116:117], v[120:121], v[116:117] op_sel_hi:[0,1]
	v_pk_mul_f32 v[112:113], v[112:113], v[116:117]
	v_pk_mul_f32 v[114:115], v[114:115], v[118:119]
	s_and_b64 vcc, exec, s[12:13]
	s_mov_b64 s[58:59], -1
	s_cbranch_vccnz .LBB0_166

; __device__ __forceinline__ void phase_inproj(const Params& p, char* smem) {
;     ...
;         if (q8) {
;           const float rs = ((const float*)(ws + OFF_SXH))[row];
;           const float4 cw = *(const float4*)((const float*)(ws + OFF_SW8) + nt * 128 + c0);
;           v[0] *= rs * cw.x; v[1] *= rs * cw.y; v[2] *= rs * cw.z; v[3] *= rs * cw.w;
;         }
.LBB0_318:
	v_mov_b32_e32 v122, v165
	v_mov_b64_e32 v[108:109], v[152:153]
	v_mov_b64_e32 v[110:111], v[154:155]
	v_pk_mul_f32 v[110:111], v[122:123], v[110:111] op_sel_hi:[0,1]
	v_pk_mul_f32 v[108:109], v[122:123], v[108:109] op_sel_hi:[0,1]
	v_pk_mul_f32 v[104:105], v[104:105], v[108:109]
	v_pk_mul_f32 v[106:107], v[106:107], v[110:111]
	s_and_b64 vcc, exec, s[12:13]
	s_mov_b64 s[58:59], -1
	s_cbranch_vccnz .LBB0_174

; __device__ __forceinline__ void phase_inproj(const Params& p, char* smem) {
;     ...
;         if (q8) {
;           const float rs = ((const float*)(ws + OFF_SXH))[row];
;           const float4 cw = *(const float4*)((const float*)(ws + OFF_SW8) + nt * 128 + c0);
;           v[0] *= rs * cw.x; v[1] *= rs * cw.y; v[2] *= rs * cw.z; v[3] *= rs * cw.w;
;         }
.LBB0_331:
	v_mov_b32_e32 v108, v165
	v_mov_b64_e32 v[104:105], v[156:157]
	v_mov_b64_e32 v[106:107], v[158:159]
	v_pk_mul_f32 v[106:107], v[108:109], v[106:107] op_sel_hi:[0,1]
	v_pk_mul_f32 v[104:105], v[108:109], v[104:105] op_sel_hi:[0,1]
	v_pk_mul_f32 v[100:101], v[100:101], v[104:105]
	v_pk_mul_f32 v[102:103], v[102:103], v[106:107]
	s_and_b64 vcc, exec, s[12:13]
	s_mov_b64 s[58:59], -1
	s_cbranch_vccnz .LBB0_177

; __device__ __forceinline__ void phase_inproj(const Params& p, char* smem) {
;     ...
;         if (q8) {
;           const float rs = ((const float*)(ws + OFF_SXH))[row];
;           const float4 cw = *(const float4*)((const float*)(ws + OFF_SW8) + nt * 128 + c0);
;           v[0] *= rs * cw.x; v[1] *= rs * cw.y; v[2] *= rs * cw.z; v[3] *= rs * cw.w;
;         }
.LBB0_344:
	v_mov_b32_e32 v104, v165
	v_mov_b64_e32 v[100:101], v[160:161]
	v_mov_b64_e32 v[102:103], v[162:163]
	v_pk_mul_f32 v[102:103], v[104:105], v[102:103] op_sel_hi:[0,1]
	v_pk_mul_f32 v[100:101], v[104:105], v[100:101] op_sel_hi:[0,1]
	v_pk_mul_f32 v[96:97], v[96:97], v[100:101]
	v_pk_mul_f32 v[98:99], v[98:99], v[102:103]
	s_and_b64 vcc, exec, s[12:13]
	s_mov_b64 s[58:59], -1
	s_cbranch_vccnz .LBB0_180

; __device__ __forceinline__ void phase_inproj(const Params& p, char* smem) {
;     ...
;         if (q8) {
;           const float rs = ((const float*)(ws + OFF_SXH))[row];
;           const float4 cw = *(const float4*)((const float*)(ws + OFF_SW8) + nt * 128 + c0);
;           v[0] *= rs * cw.x; v[1] *= rs * cw.y; v[2] *= rs * cw.z; v[3] *= rs * cw.w;
;         }
.LBB0_372:
	v_mov_b32_e32 v106, v166
	v_mov_b64_e32 v[92:93], v[152:153]
	v_mov_b64_e32 v[94:95], v[154:155]
	v_pk_mul_f32 v[94:95], v[106:107], v[94:95] op_sel_hi:[0,1]
	v_pk_mul_f32 v[92:93], v[106:107], v[92:93] op_sel_hi:[0,1]
	v_pk_mul_f32 v[88:89], v[88:89], v[92:93]
	v_pk_mul_f32 v[90:91], v[90:91], v[94:95]
	s_and_b64 vcc, exec, s[12:13]
	s_mov_b64 s[58:59], -1
	s_cbranch_vccnz .LBB0_188

; __device__ __forceinline__ void phase_inproj(const Params& p, char* smem) {
;     ...
;         if (q8) {
;           const float rs = ((const float*)(ws + OFF_SXH))[row];
;           const float4 cw = *(const float4*)((const float*)(ws + OFF_SW8) + nt * 128 + c0);
;           v[0] *= rs * cw.x; v[1] *= rs * cw.y; v[2] *= rs * cw.z; v[3] *= rs * cw.w;
;         }
.LBB0_385:
	v_mov_b32_e32 v92, v166
	v_mov_b64_e32 v[88:89], v[156:157]
	v_mov_b64_e32 v[90:91], v[158:159]
	v_pk_mul_f32 v[90:91], v[92:93], v[90:91] op_sel_hi:[0,1]
	v_pk_mul_f32 v[88:89], v[92:93], v[88:89] op_sel_hi:[0,1]
	v_pk_mul_f32 v[84:85], v[84:85], v[88:89]
	v_pk_mul_f32 v[86:87], v[86:87], v[90:91]
	s_and_b64 vcc, exec, s[12:13]
	s_mov_b64 s[58:59], -1
	s_cbranch_vccnz .LBB0_191

; __device__ __forceinline__ void phase_inproj(const Params& p, char* smem) {
;     ...
;         if (q8) {
;           const float rs = ((const float*)(ws + OFF_SXH))[row];
;           const float4 cw = *(const float4*)((const float*)(ws + OFF_SW8) + nt * 128 + c0);
;           v[0] *= rs * cw.x; v[1] *= rs * cw.y; v[2] *= rs * cw.z; v[3] *= rs * cw.w;
;         }
.LBB0_398:
	v_mov_b32_e32 v88, v166
	v_mov_b64_e32 v[84:85], v[160:161]
	v_mov_b64_e32 v[86:87], v[162:163]
	v_pk_mul_f32 v[86:87], v[88:89], v[86:87] op_sel_hi:[0,1]
	v_pk_mul_f32 v[84:85], v[88:89], v[84:85] op_sel_hi:[0,1]
	v_pk_mul_f32 v[80:81], v[80:81], v[84:85]
	v_pk_mul_f32 v[82:83], v[82:83], v[86:87]
	s_and_b64 vcc, exec, s[12:13]
	s_mov_b64 s[58:59], -1
	s_cbranch_vccnz .LBB0_194

; __device__ __forceinline__ void phase_inproj(const Params& p, char* smem) {
;     ...
;         if (q8) {
;           const float rs = ((const float*)(ws + OFF_SXH))[row];
;           const float4 cw = *(const float4*)((const float*)(ws + OFF_SW8) + nt * 128 + c0);
;           v[0] *= rs * cw.x; v[1] *= rs * cw.y; v[2] *= rs * cw.z; v[3] *= rs * cw.w;
;         }
.LBB0_426:
	v_mov_b32_e32 v90, v167
	v_mov_b64_e32 v[76:77], v[152:153]
	v_mov_b64_e32 v[78:79], v[154:155]
	v_pk_mul_f32 v[78:79], v[90:91], v[78:79] op_sel_hi:[0,1]
	v_pk_mul_f32 v[76:77], v[90:91], v[76:77] op_sel_hi:[0,1]
	v_pk_mul_f32 v[72:73], v[72:73], v[76:77]
	v_pk_mul_f32 v[74:75], v[74:75], v[78:79]
	s_and_b64 vcc, exec, s[12:13]
	s_mov_b64 s[58:59], -1
	s_cbranch_vccnz .LBB0_202

; __device__ __forceinline__ void phase_inproj(const Params& p, char* smem) {
;     ...
;         if (q8) {
;           const float rs = ((const float*)(ws + OFF_SXH))[row];
;           const float4 cw = *(const float4*)((const float*)(ws + OFF_SW8) + nt * 128 + c0);
;           v[0] *= rs * cw.x; v[1] *= rs * cw.y; v[2] *= rs * cw.z; v[3] *= rs * cw.w;
;         }
.LBB0_439:
	v_mov_b32_e32 v76, v167
	v_mov_b64_e32 v[72:73], v[156:157]
	v_mov_b64_e32 v[74:75], v[158:159]
	v_pk_mul_f32 v[74:75], v[76:77], v[74:75] op_sel_hi:[0,1]
	v_pk_mul_f32 v[72:73], v[76:77], v[72:73] op_sel_hi:[0,1]
	v_pk_mul_f32 v[68:69], v[68:69], v[72:73]
	v_pk_mul_f32 v[70:71], v[70:71], v[74:75]
	s_and_b64 vcc, exec, s[12:13]
	s_mov_b64 s[58:59], -1
	s_cbranch_vccnz .LBB0_205

; __device__ __forceinline__ void phase_inproj(const Params& p, char* smem) {
;     ...
;         if (q8) {
;           const float rs = ((const float*)(ws + OFF_SXH))[row];
;           const float4 cw = *(const float4*)((const float*)(ws + OFF_SW8) + nt * 128 + c0);
;           v[0] *= rs * cw.x; v[1] *= rs * cw.y; v[2] *= rs * cw.z; v[3] *= rs * cw.w;
;         }
.LBB0_452:
	v_mov_b32_e32 v72, v167
	v_mov_b64_e32 v[68:69], v[160:161]
	v_mov_b64_e32 v[70:71], v[162:163]
	v_pk_mul_f32 v[70:71], v[72:73], v[70:71] op_sel_hi:[0,1]
	v_pk_mul_f32 v[68:69], v[72:73], v[68:69] op_sel_hi:[0,1]
	v_pk_mul_f32 v[64:65], v[64:65], v[68:69]
	v_pk_mul_f32 v[66:67], v[66:67], v[70:71]
	s_and_b64 vcc, exec, s[12:13]
	s_mov_b64 s[58:59], -1
	s_cbranch_vccnz .LBB0_208

; __device__ __forceinline__ void phase_inproj(const Params& p, char* smem) {
;     ...
;         if (q8) {
;           const float rs = ((const float*)(ws + OFF_SXH))[row];
;           const float4 cw = *(const float4*)((const float*)(ws + OFF_SW8) + nt * 128 + c0);
;           v[0] *= rs * cw.x; v[1] *= rs * cw.y; v[2] *= rs * cw.z; v[3] *= rs * cw.w;
;         }
.LBB0_480:
	v_mov_b32_e32 v74, v168
	v_mov_b64_e32 v[60:61], v[152:153]
	v_mov_b64_e32 v[62:63], v[154:155]
	v_pk_mul_f32 v[62:63], v[74:75], v[62:63] op_sel_hi:[0,1]
	v_pk_mul_f32 v[60:61], v[74:75], v[60:61] op_sel_hi:[0,1]
	v_pk_mul_f32 v[56:57], v[56:57], v[60:61]
	v_pk_mul_f32 v[58:59], v[58:59], v[62:63]
	s_and_b64 vcc, exec, s[12:13]
	s_mov_b64 s[58:59], -1
	s_cbranch_vccnz .LBB0_216

; __device__ __forceinline__ void phase_inproj(const Params& p, char* smem) {
;     ...
;         if (q8) {
;           const float rs = ((const float*)(ws + OFF_SXH))[row];
;           const float4 cw = *(const float4*)((const float*)(ws + OFF_SW8) + nt * 128 + c0);
;           v[0] *= rs * cw.x; v[1] *= rs * cw.y; v[2] *= rs * cw.z; v[3] *= rs * cw.w;
;         }
.LBB0_493:
	v_mov_b32_e32 v60, v168
	v_mov_b64_e32 v[56:57], v[156:157]
	v_mov_b64_e32 v[58:59], v[158:159]
	v_pk_mul_f32 v[58:59], v[60:61], v[58:59] op_sel_hi:[0,1]
	v_pk_mul_f32 v[56:57], v[60:61], v[56:57] op_sel_hi:[0,1]
	v_pk_mul_f32 v[52:53], v[52:53], v[56:57]
	v_pk_mul_f32 v[54:55], v[54:55], v[58:59]
	s_and_b64 vcc, exec, s[12:13]
	s_mov_b64 s[58:59], -1
	s_cbranch_vccnz .LBB0_219

; __device__ __forceinline__ void phase_inproj(const Params& p, char* smem) {
;     ...
;         if (q8) {
;           const float rs = ((const float*)(ws + OFF_SXH))[row];
;           const float4 cw = *(const float4*)((const float*)(ws + OFF_SW8) + nt * 128 + c0);
;           v[0] *= rs * cw.x; v[1] *= rs * cw.y; v[2] *= rs * cw.z; v[3] *= rs * cw.w;
;         }
.LBB0_506:
	v_mov_b32_e32 v56, v168
	v_mov_b64_e32 v[52:53], v[160:161]
	v_mov_b64_e32 v[54:55], v[162:163]
	v_pk_mul_f32 v[54:55], v[56:57], v[54:55] op_sel_hi:[0,1]
	v_pk_mul_f32 v[52:53], v[56:57], v[52:53] op_sel_hi:[0,1]
	v_pk_mul_f32 v[48:49], v[48:49], v[52:53]
	v_pk_mul_f32 v[50:51], v[50:51], v[54:55]
	s_and_b64 vcc, exec, s[12:13]
	s_mov_b64 s[58:59], -1
	s_cbranch_vccnz .LBB0_222

; __device__ __forceinline__ void phase_inproj(const Params& p, char* smem) {
;     ...
;         if (q8) {
;           const float rs = ((const float*)(ws + OFF_SXH))[row];
;           const float4 cw = *(const float4*)((const float*)(ws + OFF_SW8) + nt * 128 + c0);
;           v[0] *= rs * cw.x; v[1] *= rs * cw.y; v[2] *= rs * cw.z; v[3] *= rs * cw.w;
;         }
.LBB0_534:
	v_mov_b32_e32 v58, v169
	v_mov_b64_e32 v[44:45], v[152:153]
	v_mov_b64_e32 v[46:47], v[154:155]
	v_pk_mul_f32 v[46:47], v[58:59], v[46:47] op_sel_hi:[0,1]
	v_pk_mul_f32 v[44:45], v[58:59], v[44:45] op_sel_hi:[0,1]
	v_pk_mul_f32 v[40:41], v[40:41], v[44:45]
	v_pk_mul_f32 v[42:43], v[42:43], v[46:47]
	s_and_b64 vcc, exec, s[12:13]
	s_mov_b64 s[58:59], -1
	s_cbranch_vccnz .LBB0_230

; __device__ __forceinline__ void phase_inproj(const Params& p, char* smem) {
;     ...
;         if (q8) {
;           const float rs = ((const float*)(ws + OFF_SXH))[row];
;           const float4 cw = *(const float4*)((const float*)(ws + OFF_SW8) + nt * 128 + c0);
;           v[0] *= rs * cw.x; v[1] *= rs * cw.y; v[2] *= rs * cw.z; v[3] *= rs * cw.w;
;         }
.LBB0_547:
	v_mov_b32_e32 v44, v169
	v_mov_b64_e32 v[40:41], v[156:157]
	v_mov_b64_e32 v[42:43], v[158:159]
	v_pk_mul_f32 v[42:43], v[44:45], v[42:43] op_sel_hi:[0,1]
	v_pk_mul_f32 v[40:41], v[44:45], v[40:41] op_sel_hi:[0,1]
	v_pk_mul_f32 v[36:37], v[36:37], v[40:41]
	v_pk_mul_f32 v[38:39], v[38:39], v[42:43]
	s_and_b64 vcc, exec, s[12:13]
	s_mov_b64 s[58:59], -1
	s_cbranch_vccnz .LBB0_233

; __device__ __forceinline__ void phase_inproj(const Params& p, char* smem) {
;     ...
;         if (q8) {
;           const float rs = ((const float*)(ws + OFF_SXH))[row];
;           const float4 cw = *(const float4*)((const float*)(ws + OFF_SW8) + nt * 128 + c0);
;           v[0] *= rs * cw.x; v[1] *= rs * cw.y; v[2] *= rs * cw.z; v[3] *= rs * cw.w;
;         }
.LBB0_560:
	v_mov_b32_e32 v40, v169
	v_mov_b64_e32 v[36:37], v[160:161]
	v_mov_b64_e32 v[38:39], v[162:163]
	v_pk_mul_f32 v[38:39], v[40:41], v[38:39] op_sel_hi:[0,1]
	v_pk_mul_f32 v[36:37], v[40:41], v[36:37] op_sel_hi:[0,1]
	v_pk_mul_f32 v[32:33], v[32:33], v[36:37]
	v_pk_mul_f32 v[34:35], v[34:35], v[38:39]
	s_and_b64 vcc, exec, s[12:13]
	s_mov_b64 s[58:59], -1
	s_cbranch_vccnz .LBB0_236

; __device__ __forceinline__ void phase_inproj(const Params& p, char* smem) {
;     ...
;         if (q8) {
;           const float rs = ((const float*)(ws + OFF_SXH))[row];
;           const float4 cw = *(const float4*)((const float*)(ws + OFF_SW8) + nt * 128 + c0);
;           v[0] *= rs * cw.x; v[1] *= rs * cw.y; v[2] *= rs * cw.z; v[3] *= rs * cw.w;
;         }
.LBB0_588:
	v_mov_b32_e32 v42, v170
	v_mov_b64_e32 v[28:29], v[152:153]
	v_mov_b64_e32 v[30:31], v[154:155]
	v_pk_mul_f32 v[30:31], v[42:43], v[30:31] op_sel_hi:[0,1]
	v_pk_mul_f32 v[28:29], v[42:43], v[28:29] op_sel_hi:[0,1]
	v_pk_mul_f32 v[24:25], v[24:25], v[28:29]
	v_pk_mul_f32 v[26:27], v[26:27], v[30:31]
	s_and_b64 vcc, exec, s[12:13]
	s_mov_b64 s[58:59], -1
	s_cbranch_vccnz .LBB0_244

; __device__ __forceinline__ void phase_inproj(const Params& p, char* smem) {
;     ...
;         if (q8) {
;           const float rs = ((const float*)(ws + OFF_SXH))[row];
;           const float4 cw = *(const float4*)((const float*)(ws + OFF_SW8) + nt * 128 + c0);
;           v[0] *= rs * cw.x; v[1] *= rs * cw.y; v[2] *= rs * cw.z; v[3] *= rs * cw.w;
;         }
.LBB0_601:
	v_mov_b32_e32 v28, v170
	v_mov_b64_e32 v[24:25], v[156:157]
	v_mov_b64_e32 v[26:27], v[158:159]
	v_pk_mul_f32 v[26:27], v[28:29], v[26:27] op_sel_hi:[0,1]
	v_pk_mul_f32 v[24:25], v[28:29], v[24:25] op_sel_hi:[0,1]
	v_pk_mul_f32 v[20:21], v[20:21], v[24:25]
	v_pk_mul_f32 v[22:23], v[22:23], v[26:27]
	s_and_b64 vcc, exec, s[12:13]
	s_mov_b64 s[58:59], -1
	s_cbranch_vccnz .LBB0_247

; __device__ __forceinline__ void phase_inproj(const Params& p, char* smem) {
;     ...
;         if (q8) {
;           const float rs = ((const float*)(ws + OFF_SXH))[row];
;           const float4 cw = *(const float4*)((const float*)(ws + OFF_SW8) + nt * 128 + c0);
;           v[0] *= rs * cw.x; v[1] *= rs * cw.y; v[2] *= rs * cw.z; v[3] *= rs * cw.w;
;         }
.LBB0_614:
	v_mov_b32_e32 v24, v170
	v_mov_b64_e32 v[20:21], v[160:161]
	v_mov_b64_e32 v[22:23], v[162:163]
	v_pk_mul_f32 v[22:23], v[24:25], v[22:23] op_sel_hi:[0,1]
	v_pk_mul_f32 v[20:21], v[24:25], v[20:21] op_sel_hi:[0,1]
	v_pk_mul_f32 v[16:17], v[16:17], v[20:21]
	v_pk_mul_f32 v[18:19], v[18:19], v[22:23]
	s_and_b64 vcc, exec, s[12:13]
	s_mov_b64 s[58:59], -1
	s_cbranch_vccnz .LBB0_250

; __device__ __forceinline__ void phase_inproj(const Params& p, char* smem) {
;     ...
;         if (q8) {
;           const float rs = ((const float*)(ws + OFF_SXH))[row];
;           const float4 cw = *(const float4*)((const float*)(ws + OFF_SW8) + nt * 128 + c0);
;           v[0] *= rs * cw.x; v[1] *= rs * cw.y; v[2] *= rs * cw.z; v[3] *= rs * cw.w;
;         }
.LBB0_642:
	v_mov_b32_e32 v26, v171
	v_mov_b64_e32 v[12:13], v[152:153]
	v_mov_b64_e32 v[14:15], v[154:155]
	v_pk_mul_f32 v[14:15], v[26:27], v[14:15] op_sel_hi:[0,1]
	v_pk_mul_f32 v[12:13], v[26:27], v[12:13] op_sel_hi:[0,1]
	v_pk_mul_f32 v[8:9], v[8:9], v[12:13]
	v_pk_mul_f32 v[10:11], v[10:11], v[14:15]
	s_and_b64 vcc, exec, s[12:13]
	s_mov_b64 s[40:41], -1
	s_cbranch_vccnz .LBB0_258

; __device__ __forceinline__ void phase_inproj(const Params& p, char* smem) {
;     ...
;         if (q8) {
;           const float rs = ((const float*)(ws + OFF_SXH))[row];
;           const float4 cw = *(const float4*)((const float*)(ws + OFF_SW8) + nt * 128 + c0);
;           v[0] *= rs * cw.x; v[1] *= rs * cw.y; v[2] *= rs * cw.z; v[3] *= rs * cw.w;
;         }
.LBB0_655:
	v_mov_b32_e32 v12, v171
	v_mov_b64_e32 v[8:9], v[156:157]
	v_mov_b64_e32 v[10:11], v[158:159]
	v_pk_mul_f32 v[10:11], v[12:13], v[10:11] op_sel_hi:[0,1]
	v_pk_mul_f32 v[8:9], v[12:13], v[8:9] op_sel_hi:[0,1]
	v_pk_mul_f32 v[4:5], v[4:5], v[8:9]
	v_pk_mul_f32 v[6:7], v[6:7], v[10:11]
	s_and_b64 vcc, exec, s[12:13]
	s_mov_b64 s[40:41], -1
	s_cbranch_vccnz .LBB0_261

; __device__ __forceinline__ void phase_inproj(const Params& p, char* smem) {
;     ...
;         if (q8) {
;           const float rs = ((const float*)(ws + OFF_SXH))[row];
;           const float4 cw = *(const float4*)((const float*)(ws + OFF_SW8) + nt * 128 + c0);
;           v[0] *= rs * cw.x; v[1] *= rs * cw.y; v[2] *= rs * cw.z; v[3] *= rs * cw.w;
;         }
.LBB0_668:
	v_mov_b32_e32 v8, v171
	v_mov_b64_e32 v[4:5], v[160:161]
	v_mov_b64_e32 v[6:7], v[162:163]
	v_pk_mul_f32 v[6:7], v[8:9], v[6:7] op_sel_hi:[0,1]
	v_pk_mul_f32 v[4:5], v[8:9], v[4:5] op_sel_hi:[0,1]
	v_pk_mul_f32 v[0:1], v[0:1], v[4:5]
	v_pk_mul_f32 v[2:3], v[2:3], v[6:7]
	s_and_b64 vcc, exec, s[12:13]
	s_mov_b64 s[8:9], -1
	s_cbranch_vccnz .LBB0_264

; __device__ __forceinline__ float lo_bf(unsigned u) { return __uint_as_float(u << 16); }
; __device__ __forceinline__ float hi_bf(unsigned u) { return __uint_as_float(u & 0xffff0000u); }
; __device__ __forceinline__ void phase_merge(const Params& p, char* smem) {
;     ...
;       for (int m = 0; m < 8; ++m)
; #pragma unroll
;         for (int n = 0; n < 4; ++n) {
;           const size_t row = (size_t)mt2 * 256 + wr * 128 + m * 16 + fr;
;           const int col = nt2 * 128 + wc * 64 + n * 16 + fq * 4;
;           const uint2 g = *(const uint2*)(G + row * 2048 + col);
;           float v0 = acc[m][n][0] * lo_bf(g.x), v1 = acc[m][n][1] * hi_bf(g.x);
;           float v2 = acc[m][n][2] * lo_bf(g.y), v3 = acc[m][n][3] * hi_bf(g.y);
;           if (pass) {
;             const uint2 pm = *(const uint2*)(mg + row * 2048 + col);
;             v0 += lo_bf(pm.x); v1 += hi_bf(pm.x); v2 += lo_bf(pm.y); v3 += hi_bf(pm.y);
;           }
;           uint2 o; o.x = pack2(v0, v1); o.y = pack2(v2, v3);
;           *(uint2*)(mg + row * 2048 + col) = o;
;         }
.LBB0_953:
	s_and_b64 s[6:7], s[8:9], exec
	s_cselect_b32 s6, s27, 0x30c00000
	s_add_u32 s10, s54, s6
	s_mov_b32 s49, s45
	s_mov_b32 s6, s46
	s_addc_u32 s11, s55, 0
	s_barrier
	s_ashr_i32 s7, s6, 31
	s_lshl_b64 s[6:7], s[6:7], 19
	s_waitcnt vmcnt(0)
	v_lshl_add_u64 v[106:107], s[6:7], 0, v[176:177]
	v_lshl_or_b32 v104, s49, 7, v192
	v_add_lshl_u32 v226, v106, v104, 1
	s_andn2_b64 vcc, exec, s[12:13]
	s_cbranch_vccnz .Lmg_p0
	s_add_u32 s98, s10, 0x0
	s_addc_u32 s99, s11, 0
	s_add_u32 s100, s40, 0x0
	s_addc_u32 s101, s41, 0
	global_load_dwordx2 v[104:105], v226, s[98:99]
	global_load_dwordx2 v[106:107], v226, s[98:99] offset:32
	global_load_dwordx2 v[108:109], v226, s[98:99] offset:64
	global_load_dwordx2 v[110:111], v226, s[98:99] offset:96
	s_add_u32 s98, s98, 0x10000
	s_addc_u32 s99, s99, 0
	global_load_dwordx2 v[112:113], v226, s[98:99]
	global_load_dwordx2 v[114:115], v226, s[98:99] offset:32
	global_load_dwordx2 v[116:117], v226, s[98:99] offset:64
	global_load_dwordx2 v[118:119], v226, s[98:99] offset:96
	s_add_u32 s98, s98, 0x10000
	s_addc_u32 s99, s99, 0
	global_load_dwordx2 v[124:125], v226, s[98:99]
	global_load_dwordx2 v[126:127], v226, s[98:99] offset:32
	global_load_dwordx2 v[128:129], v226, s[98:99] offset:64
	global_load_dwordx2 v[130:131], v226, s[98:99] offset:96
	s_add_u32 s98, s98, 0x10000
	s_addc_u32 s99, s99, 0
	global_load_dwordx2 v[132:133], v226, s[98:99]
	global_load_dwordx2 v[134:135], v226, s[98:99] offset:32
	global_load_dwordx2 v[136:137], v226, s[98:99] offset:64
	global_load_dwordx2 v[138:139], v226, s[98:99] offset:96
	global_load_dwordx2 v[140:141], v226, s[100:101]
	global_load_dwordx2 v[142:143], v226, s[100:101] offset:32
	global_load_dwordx2 v[144:145], v226, s[100:101] offset:64
	global_load_dwordx2 v[146:147], v226, s[100:101] offset:96
	s_add_u32 s100, s100, 0x10000
	s_addc_u32 s101, s101, 0
	global_load_dwordx2 v[148:149], v226, s[100:101]
	global_load_dwordx2 v[150:151], v226, s[100:101] offset:32
	global_load_dwordx2 v[152:153], v226, s[100:101] offset:64
	global_load_dwordx2 v[154:155], v226, s[100:101] offset:96
	s_add_u32 s100, s100, 0x10000
	s_addc_u32 s101, s101, 0
	global_load_dwordx2 v[198:199], v226, s[100:101]
	global_load_dwordx2 v[200:201], v226, s[100:101] offset:32
	global_load_dwordx2 v[202:203], v226, s[100:101] offset:64
	global_load_dwordx2 v[204:205], v226, s[100:101] offset:96
	s_add_u32 s100, s100, 0x10000
	s_addc_u32 s101, s101, 0
	global_load_dwordx2 v[206:207], v226, s[100:101]
	global_load_dwordx2 v[208:209], v226, s[100:101] offset:32
	global_load_dwordx2 v[210:211], v226, s[100:101] offset:64
	global_load_dwordx2 v[212:213], v226, s[100:101] offset:96
	s_waitcnt vmcnt(0)
	s_add_u32 s100, s40, 0x0
	s_addc_u32 s101, s41, 0
	v_lshlrev_b32_e32 v218, 16, v104
	v_and_b32_e32 v219, 0xffff0000, v104
	v_lshlrev_b32_e32 v220, 16, v105
	v_and_b32_e32 v221, 0xffff0000, v105
	v_pk_mul_f32 v[218:219], v[172:173], v[218:219]
	v_pk_mul_f32 v[220:221], v[174:175], v[220:221]
	v_lshlrev_b32_e32 v222, 16, v140
	v_and_b32_e32 v223, 0xffff0000, v140
	v_lshlrev_b32_e32 v224, 16, v141
	v_and_b32_e32 v225, 0xffff0000, v141
	v_pk_add_f32 v[218:219], v[218:219], v[222:223]
	v_pk_add_f32 v[220:221], v[220:221], v[224:225]
	v_cvt_pk_bf16_f32 v104, v218, v219
	v_cvt_pk_bf16_f32 v105, v220, v221
	global_store_dwordx2 v226, v[104:105], s[100:101]
	v_lshlrev_b32_e32 v218, 16, v106
	v_and_b32_e32 v219, 0xffff0000, v106
	v_lshlrev_b32_e32 v220, 16, v107
	v_and_b32_e32 v221, 0xffff0000, v107
	v_pk_mul_f32 v[218:219], v[168:169], v[218:219]
	v_pk_mul_f32 v[220:221], v[170:171], v[220:221]
	v_lshlrev_b32_e32 v222, 16, v142
	v_and_b32_e32 v223, 0xffff0000, v142
	v_lshlrev_b32_e32 v224, 16, v143
	v_and_b32_e32 v225, 0xffff0000, v143
	v_pk_add_f32 v[218:219], v[218:219], v[222:223]
	v_pk_add_f32 v[220:221], v[220:221], v[224:225]
	v_cvt_pk_bf16_f32 v106, v218, v219
	v_cvt_pk_bf16_f32 v107, v220, v221
	global_store_dwordx2 v226, v[106:107], s[100:101] offset:32
	v_lshlrev_b32_e32 v218, 16, v108
	v_and_b32_e32 v219, 0xffff0000, v108
	v_lshlrev_b32_e32 v220, 16, v109
	v_and_b32_e32 v221, 0xffff0000, v109
	v_pk_mul_f32 v[218:219], v[164:165], v[218:219]
	v_pk_mul_f32 v[220:221], v[166:167], v[220:221]
	v_lshlrev_b32_e32 v222, 16, v144
	v_and_b32_e32 v223, 0xffff0000, v144
	v_lshlrev_b32_e32 v224, 16, v145
	v_and_b32_e32 v225, 0xffff0000, v145
	v_pk_add_f32 v[218:219], v[218:219], v[222:223]
	v_pk_add_f32 v[220:221], v[220:221], v[224:225]
	v_cvt_pk_bf16_f32 v108, v218, v219
	v_cvt_pk_bf16_f32 v109, v220, v221
	global_store_dwordx2 v226, v[108:109], s[100:101] offset:64
	v_lshlrev_b32_e32 v218, 16, v110
	v_and_b32_e32 v219, 0xffff0000, v110
	v_lshlrev_b32_e32 v220, 16, v111
	v_and_b32_e32 v221, 0xffff0000, v111
	v_pk_mul_f32 v[218:219], v[160:161], v[218:219]
	v_pk_mul_f32 v[220:221], v[162:163], v[220:221]
	v_lshlrev_b32_e32 v222, 16, v146
	v_and_b32_e32 v223, 0xffff0000, v146
	v_lshlrev_b32_e32 v224, 16, v147
	v_and_b32_e32 v225, 0xffff0000, v147
	v_pk_add_f32 v[218:219], v[218:219], v[222:223]
	v_pk_add_f32 v[220:221], v[220:221], v[224:225]
	v_cvt_pk_bf16_f32 v110, v218, v219
	v_cvt_pk_bf16_f32 v111, v220, v221
	global_store_dwordx2 v226, v[110:111], s[100:101] offset:96
	s_add_u32 s100, s100, 0x10000
	s_addc_u32 s101, s101, 0
	v_lshlrev_b32_e32 v218, 16, v112
	v_and_b32_e32 v219, 0xffff0000, v112
	v_lshlrev_b32_e32 v220, 16, v113
	v_and_b32_e32 v221, 0xffff0000, v113
	v_pk_mul_f32 v[218:219], v[156:157], v[218:219]
	v_pk_mul_f32 v[220:221], v[158:159], v[220:221]
	v_lshlrev_b32_e32 v222, 16, v148
	v_and_b32_e32 v223, 0xffff0000, v148
	v_lshlrev_b32_e32 v224, 16, v149
	v_and_b32_e32 v225, 0xffff0000, v149
; __device__ __forceinline__ float lo_bf(unsigned u) { return __uint_as_float(u << 16); }
; __device__ __forceinline__ float hi_bf(unsigned u) { return __uint_as_float(u & 0xffff0000u); }
; __device__ __forceinline__ void phase_merge(const Params& p, char* smem) {
;     ...
;       for (int m = 0; m < 8; ++m)
; #pragma unroll
;         for (int n = 0; n < 4; ++n) {
;           const size_t row = (size_t)mt2 * 256 + wr * 128 + m * 16 + fr;
;           const int col = nt2 * 128 + wc * 64 + n * 16 + fq * 4;
;           const uint2 g = *(const uint2*)(G + row * 2048 + col);
;           float v0 = acc[m][n][0] * lo_bf(g.x), v1 = acc[m][n][1] * hi_bf(g.x);
;           float v2 = acc[m][n][2] * lo_bf(g.y), v3 = acc[m][n][3] * hi_bf(g.y);
;           if (pass) {
;             const uint2 pm = *(const uint2*)(mg + row * 2048 + col);
;             v0 += lo_bf(pm.x); v1 += hi_bf(pm.x); v2 += lo_bf(pm.y); v3 += hi_bf(pm.y);
;           }
;           uint2 o; o.x = pack2(v0, v1); o.y = pack2(v2, v3);
;           *(uint2*)(mg + row * 2048 + col) = o;
;         }
	v_pk_add_f32 v[218:219], v[218:219], v[222:223]
	v_pk_add_f32 v[220:221], v[220:221], v[224:225]
	v_cvt_pk_bf16_f32 v112, v218, v219
	v_cvt_pk_bf16_f32 v113, v220, v221
	global_store_dwordx2 v226, v[112:113], s[100:101]
	v_lshlrev_b32_e32 v218, 16, v114
	v_and_b32_e32 v219, 0xffff0000, v114
	v_lshlrev_b32_e32 v220, 16, v115
	v_and_b32_e32 v221, 0xffff0000, v115
	v_pk_mul_f32 v[218:219], v[120:121], v[218:219]
	v_pk_mul_f32 v[220:221], v[122:123], v[220:221]
	v_lshlrev_b32_e32 v222, 16, v150
	v_and_b32_e32 v223, 0xffff0000, v150
	v_lshlrev_b32_e32 v224, 16, v151
	v_and_b32_e32 v225, 0xffff0000, v151
	v_pk_add_f32 v[218:219], v[218:219], v[222:223]
	v_pk_add_f32 v[220:221], v[220:221], v[224:225]
	v_cvt_pk_bf16_f32 v114, v218, v219
	v_cvt_pk_bf16_f32 v115, v220, v221
	global_store_dwordx2 v226, v[114:115], s[100:101] offset:32
	v_lshlrev_b32_e32 v218, 16, v116
	v_and_b32_e32 v219, 0xffff0000, v116
	v_lshlrev_b32_e32 v220, 16, v117
	v_and_b32_e32 v221, 0xffff0000, v117
	v_pk_mul_f32 v[218:219], v[100:101], v[218:219]
	v_pk_mul_f32 v[220:221], v[102:103], v[220:221]
	v_lshlrev_b32_e32 v222, 16, v152
	v_and_b32_e32 v223, 0xffff0000, v152
	v_lshlrev_b32_e32 v224, 16, v153
	v_and_b32_e32 v225, 0xffff0000, v153
	v_pk_add_f32 v[218:219], v[218:219], v[222:223]
	v_pk_add_f32 v[220:221], v[220:221], v[224:225]
	v_cvt_pk_bf16_f32 v116, v218, v219
	v_cvt_pk_bf16_f32 v117, v220, v221
	global_store_dwordx2 v226, v[116:117], s[100:101] offset:64
	v_lshlrev_b32_e32 v218, 16, v118
	v_and_b32_e32 v219, 0xffff0000, v118
	v_lshlrev_b32_e32 v220, 16, v119
	v_and_b32_e32 v221, 0xffff0000, v119
	v_pk_mul_f32 v[218:219], v[96:97], v[218:219]
	v_pk_mul_f32 v[220:221], v[98:99], v[220:221]
	v_lshlrev_b32_e32 v222, 16, v154
	v_and_b32_e32 v223, 0xffff0000, v154
	v_lshlrev_b32_e32 v224, 16, v155
	v_and_b32_e32 v225, 0xffff0000, v155
	v_pk_add_f32 v[218:219], v[218:219], v[222:223]
	v_pk_add_f32 v[220:221], v[220:221], v[224:225]
	v_cvt_pk_bf16_f32 v118, v218, v219
	v_cvt_pk_bf16_f32 v119, v220, v221
	global_store_dwordx2 v226, v[118:119], s[100:101] offset:96
	s_add_u32 s100, s100, 0x10000
	s_addc_u32 s101, s101, 0
	v_lshlrev_b32_e32 v218, 16, v124
	v_and_b32_e32 v219, 0xffff0000, v124
	v_lshlrev_b32_e32 v220, 16, v125
	v_and_b32_e32 v221, 0xffff0000, v125
	v_pk_mul_f32 v[218:219], v[92:93], v[218:219]
	v_pk_mul_f32 v[220:221], v[94:95], v[220:221]
	v_lshlrev_b32_e32 v222, 16, v198
	v_and_b32_e32 v223, 0xffff0000, v198
	v_lshlrev_b32_e32 v224, 16, v199
	v_and_b32_e32 v225, 0xffff0000, v199
	v_pk_add_f32 v[218:219], v[218:219], v[222:223]
	v_pk_add_f32 v[220:221], v[220:221], v[224:225]
	v_cvt_pk_bf16_f32 v124, v218, v219
	v_cvt_pk_bf16_f32 v125, v220, v221
	global_store_dwordx2 v226, v[124:125], s[100:101]
	v_lshlrev_b32_e32 v218, 16, v126
	v_and_b32_e32 v219, 0xffff0000, v126
	v_lshlrev_b32_e32 v220, 16, v127
	v_and_b32_e32 v221, 0xffff0000, v127
	v_pk_mul_f32 v[218:219], v[88:89], v[218:219]
	v_pk_mul_f32 v[220:221], v[90:91], v[220:221]
	v_lshlrev_b32_e32 v222, 16, v200
	v_and_b32_e32 v223, 0xffff0000, v200
	v_lshlrev_b32_e32 v224, 16, v201
	v_and_b32_e32 v225, 0xffff0000, v201
	v_pk_add_f32 v[218:219], v[218:219], v[222:223]
	v_pk_add_f32 v[220:221], v[220:221], v[224:225]
	v_cvt_pk_bf16_f32 v126, v218, v219
	v_cvt_pk_bf16_f32 v127, v220, v221
	global_store_dwordx2 v226, v[126:127], s[100:101] offset:32
	v_lshlrev_b32_e32 v218, 16, v128
	v_and_b32_e32 v219, 0xffff0000, v128
	v_lshlrev_b32_e32 v220, 16, v129
	v_and_b32_e32 v221, 0xffff0000, v129
	v_pk_mul_f32 v[218:219], v[84:85], v[218:219]
	v_pk_mul_f32 v[220:221], v[86:87], v[220:221]
	v_lshlrev_b32_e32 v222, 16, v202
	v_and_b32_e32 v223, 0xffff0000, v202
	v_lshlrev_b32_e32 v224, 16, v203
	v_and_b32_e32 v225, 0xffff0000, v203
	v_pk_add_f32 v[218:219], v[218:219], v[222:223]
	v_pk_add_f32 v[220:221], v[220:221], v[224:225]
	v_cvt_pk_bf16_f32 v128, v218, v219
	v_cvt_pk_bf16_f32 v129, v220, v221
	global_store_dwordx2 v226, v[128:129], s[100:101] offset:64
	v_lshlrev_b32_e32 v218, 16, v130
	v_and_b32_e32 v219, 0xffff0000, v130
	v_lshlrev_b32_e32 v220, 16, v131
	v_and_b32_e32 v221, 0xffff0000, v131
	v_pk_mul_f32 v[218:219], v[80:81], v[218:219]
	v_pk_mul_f32 v[220:221], v[82:83], v[220:221]
	v_lshlrev_b32_e32 v222, 16, v204
	v_and_b32_e32 v223, 0xffff0000, v204
	v_lshlrev_b32_e32 v224, 16, v205
	v_and_b32_e32 v225, 0xffff0000, v205
	v_pk_add_f32 v[218:219], v[218:219], v[222:223]
	v_pk_add_f32 v[220:221], v[220:221], v[224:225]
	v_cvt_pk_bf16_f32 v130, v218, v219
	v_cvt_pk_bf16_f32 v131, v220, v221
	global_store_dwordx2 v226, v[130:131], s[100:101] offset:96
	s_add_u32 s100, s100, 0x10000
	s_addc_u32 s101, s101, 0
	v_lshlrev_b32_e32 v218, 16, v132
	v_and_b32_e32 v219, 0xffff0000, v132
	v_lshlrev_b32_e32 v220, 16, v133
	v_and_b32_e32 v221, 0xffff0000, v133
	v_pk_mul_f32 v[218:219], v[76:77], v[218:219]
	v_pk_mul_f32 v[220:221], v[78:79], v[220:221]
	v_lshlrev_b32_e32 v222, 16, v206
	v_and_b32_e32 v223, 0xffff0000, v206
	v_lshlrev_b32_e32 v224, 16, v207
	v_and_b32_e32 v225, 0xffff0000, v207
	v_pk_add_f32 v[218:219], v[218:219], v[222:223]
	v_pk_add_f32 v[220:221], v[220:221], v[224:225]
	v_cvt_pk_bf16_f32 v132, v218, v219
	v_cvt_pk_bf16_f32 v133, v220, v221
	global_store_dwordx2 v226, v[132:133], s[100:101]
	v_lshlrev_b32_e32 v218, 16, v134
	v_and_b32_e32 v219, 0xffff0000, v134
	v_lshlrev_b32_e32 v220, 16, v135
	v_and_b32_e32 v221, 0xffff0000, v135
	v_pk_mul_f32 v[218:219], v[72:73], v[218:219]
	v_pk_mul_f32 v[220:221], v[74:75], v[220:221]
	v_lshlrev_b32_e32 v222, 16, v208
	v_and_b32_e32 v223, 0xffff0000, v208
	v_lshlrev_b32_e32 v224, 16, v209
	v_and_b32_e32 v225, 0xffff0000, v209
	v_pk_add_f32 v[218:219], v[218:219], v[222:223]
; __device__ __forceinline__ float lo_bf(unsigned u) { return __uint_as_float(u << 16); }
; __device__ __forceinline__ float hi_bf(unsigned u) { return __uint_as_float(u & 0xffff0000u); }
; __device__ __forceinline__ void phase_merge(const Params& p, char* smem) {
;     ...
;       for (int m = 0; m < 8; ++m)
; #pragma unroll
;         for (int n = 0; n < 4; ++n) {
;           const size_t row = (size_t)mt2 * 256 + wr * 128 + m * 16 + fr;
;           const int col = nt2 * 128 + wc * 64 + n * 16 + fq * 4;
;           const uint2 g = *(const uint2*)(G + row * 2048 + col);
;           float v0 = acc[m][n][0] * lo_bf(g.x), v1 = acc[m][n][1] * hi_bf(g.x);
;           float v2 = acc[m][n][2] * lo_bf(g.y), v3 = acc[m][n][3] * hi_bf(g.y);
;           if (pass) {
;             const uint2 pm = *(const uint2*)(mg + row * 2048 + col);
;             v0 += lo_bf(pm.x); v1 += hi_bf(pm.x); v2 += lo_bf(pm.y); v3 += hi_bf(pm.y);
;           }
;           uint2 o; o.x = pack2(v0, v1); o.y = pack2(v2, v3);
;           *(uint2*)(mg + row * 2048 + col) = o;
;         }
	v_pk_add_f32 v[220:221], v[220:221], v[224:225]
	v_cvt_pk_bf16_f32 v134, v218, v219
	v_cvt_pk_bf16_f32 v135, v220, v221
	global_store_dwordx2 v226, v[134:135], s[100:101] offset:32
	v_lshlrev_b32_e32 v218, 16, v136
	v_and_b32_e32 v219, 0xffff0000, v136
	v_lshlrev_b32_e32 v220, 16, v137
	v_and_b32_e32 v221, 0xffff0000, v137
	v_pk_mul_f32 v[218:219], v[68:69], v[218:219]
	v_pk_mul_f32 v[220:221], v[70:71], v[220:221]
	v_lshlrev_b32_e32 v222, 16, v210
	v_and_b32_e32 v223, 0xffff0000, v210
	v_lshlrev_b32_e32 v224, 16, v211
	v_and_b32_e32 v225, 0xffff0000, v211
	v_pk_add_f32 v[218:219], v[218:219], v[222:223]
	v_pk_add_f32 v[220:221], v[220:221], v[224:225]
	v_cvt_pk_bf16_f32 v136, v218, v219
	v_cvt_pk_bf16_f32 v137, v220, v221
	global_store_dwordx2 v226, v[136:137], s[100:101] offset:64
	v_lshlrev_b32_e32 v218, 16, v138
	v_and_b32_e32 v219, 0xffff0000, v138
	v_lshlrev_b32_e32 v220, 16, v139
	v_and_b32_e32 v221, 0xffff0000, v139
	v_pk_mul_f32 v[218:219], v[64:65], v[218:219]
	v_pk_mul_f32 v[220:221], v[66:67], v[220:221]
	v_lshlrev_b32_e32 v222, 16, v212
	v_and_b32_e32 v223, 0xffff0000, v212
	v_lshlrev_b32_e32 v224, 16, v213
	v_and_b32_e32 v225, 0xffff0000, v213
	v_pk_add_f32 v[218:219], v[218:219], v[222:223]
	v_pk_add_f32 v[220:221], v[220:221], v[224:225]
	v_cvt_pk_bf16_f32 v138, v218, v219
	v_cvt_pk_bf16_f32 v139, v220, v221
	global_store_dwordx2 v226, v[138:139], s[100:101] offset:96
	s_add_u32 s98, s10, 0x40000
	s_addc_u32 s99, s11, 0
	s_add_u32 s100, s40, 0x40000
	s_addc_u32 s101, s41, 0
	global_load_dwordx2 v[104:105], v226, s[98:99]
	global_load_dwordx2 v[106:107], v226, s[98:99] offset:32
	global_load_dwordx2 v[108:109], v226, s[98:99] offset:64
	global_load_dwordx2 v[110:111], v226, s[98:99] offset:96
	s_add_u32 s98, s98, 0x10000
	s_addc_u32 s99, s99, 0
	global_load_dwordx2 v[112:113], v226, s[98:99]
	global_load_dwordx2 v[114:115], v226, s[98:99] offset:32
	global_load_dwordx2 v[116:117], v226, s[98:99] offset:64
	global_load_dwordx2 v[118:119], v226, s[98:99] offset:96
	s_add_u32 s98, s98, 0x10000
	s_addc_u32 s99, s99, 0
	global_load_dwordx2 v[124:125], v226, s[98:99]
	global_load_dwordx2 v[126:127], v226, s[98:99] offset:32
	global_load_dwordx2 v[128:129], v226, s[98:99] offset:64
	global_load_dwordx2 v[130:131], v226, s[98:99] offset:96
	s_add_u32 s98, s98, 0x10000
	s_addc_u32 s99, s99, 0
	global_load_dwordx2 v[132:133], v226, s[98:99]
	global_load_dwordx2 v[134:135], v226, s[98:99] offset:32
	global_load_dwordx2 v[136:137], v226, s[98:99] offset:64
	global_load_dwordx2 v[138:139], v226, s[98:99] offset:96
	global_load_dwordx2 v[140:141], v226, s[100:101]
	global_load_dwordx2 v[142:143], v226, s[100:101] offset:32
	global_load_dwordx2 v[144:145], v226, s[100:101] offset:64
	global_load_dwordx2 v[146:147], v226, s[100:101] offset:96
	s_add_u32 s100, s100, 0x10000
	s_addc_u32 s101, s101, 0
	global_load_dwordx2 v[148:149], v226, s[100:101]
	global_load_dwordx2 v[150:151], v226, s[100:101] offset:32
	global_load_dwordx2 v[152:153], v226, s[100:101] offset:64
	global_load_dwordx2 v[154:155], v226, s[100:101] offset:96
	s_add_u32 s100, s100, 0x10000
	s_addc_u32 s101, s101, 0
	global_load_dwordx2 v[198:199], v226, s[100:101]
	global_load_dwordx2 v[200:201], v226, s[100:101] offset:32
	global_load_dwordx2 v[202:203], v226, s[100:101] offset:64
	global_load_dwordx2 v[204:205], v226, s[100:101] offset:96
	s_add_u32 s100, s100, 0x10000
	s_addc_u32 s101, s101, 0
	global_load_dwordx2 v[206:207], v226, s[100:101]
	global_load_dwordx2 v[208:209], v226, s[100:101] offset:32
	global_load_dwordx2 v[210:211], v226, s[100:101] offset:64
	global_load_dwordx2 v[212:213], v226, s[100:101] offset:96
	s_waitcnt vmcnt(0)
	s_add_u32 s100, s40, 0x40000
	s_addc_u32 s101, s41, 0
	v_lshlrev_b32_e32 v218, 16, v104
	v_and_b32_e32 v219, 0xffff0000, v104
	v_lshlrev_b32_e32 v220, 16, v105
	v_and_b32_e32 v221, 0xffff0000, v105
	v_pk_mul_f32 v[218:219], v[60:61], v[218:219]
	v_pk_mul_f32 v[220:221], v[62:63], v[220:221]
	v_lshlrev_b32_e32 v222, 16, v140
	v_and_b32_e32 v223, 0xffff0000, v140
	v_lshlrev_b32_e32 v224, 16, v141
	v_and_b32_e32 v225, 0xffff0000, v141
	v_pk_add_f32 v[218:219], v[218:219], v[222:223]
	v_pk_add_f32 v[220:221], v[220:221], v[224:225]
	v_cvt_pk_bf16_f32 v104, v218, v219
	v_cvt_pk_bf16_f32 v105, v220, v221
	global_store_dwordx2 v226, v[104:105], s[100:101]
	v_lshlrev_b32_e32 v218, 16, v106
	v_and_b32_e32 v219, 0xffff0000, v106
	v_lshlrev_b32_e32 v220, 16, v107
	v_and_b32_e32 v221, 0xffff0000, v107
	v_pk_mul_f32 v[218:219], v[56:57], v[218:219]
	v_pk_mul_f32 v[220:221], v[58:59], v[220:221]
	v_lshlrev_b32_e32 v222, 16, v142
	v_and_b32_e32 v223, 0xffff0000, v142
	v_lshlrev_b32_e32 v224, 16, v143
	v_and_b32_e32 v225, 0xffff0000, v143
	v_pk_add_f32 v[218:219], v[218:219], v[222:223]
	v_pk_add_f32 v[220:221], v[220:221], v[224:225]
	v_cvt_pk_bf16_f32 v106, v218, v219
	v_cvt_pk_bf16_f32 v107, v220, v221
	global_store_dwordx2 v226, v[106:107], s[100:101] offset:32
	v_lshlrev_b32_e32 v218, 16, v108
	v_and_b32_e32 v219, 0xffff0000, v108
	v_lshlrev_b32_e32 v220, 16, v109
	v_and_b32_e32 v221, 0xffff0000, v109
	v_pk_mul_f32 v[218:219], v[52:53], v[218:219]
	v_pk_mul_f32 v[220:221], v[54:55], v[220:221]
	v_lshlrev_b32_e32 v222, 16, v144
	v_and_b32_e32 v223, 0xffff0000, v144
	v_lshlrev_b32_e32 v224, 16, v145
	v_and_b32_e32 v225, 0xffff0000, v145
	v_pk_add_f32 v[218:219], v[218:219], v[222:223]
	v_pk_add_f32 v[220:221], v[220:221], v[224:225]
	v_cvt_pk_bf16_f32 v108, v218, v219
	v_cvt_pk_bf16_f32 v109, v220, v221
	global_store_dwordx2 v226, v[108:109], s[100:101] offset:64
	v_lshlrev_b32_e32 v218, 16, v110
	v_and_b32_e32 v219, 0xffff0000, v110
; __device__ __forceinline__ float lo_bf(unsigned u) { return __uint_as_float(u << 16); }
; __device__ __forceinline__ float hi_bf(unsigned u) { return __uint_as_float(u & 0xffff0000u); }
; __device__ __forceinline__ void phase_merge(const Params& p, char* smem) {
;     ...
;       for (int m = 0; m < 8; ++m)
; #pragma unroll
;         for (int n = 0; n < 4; ++n) {
;           const size_t row = (size_t)mt2 * 256 + wr * 128 + m * 16 + fr;
;           const int col = nt2 * 128 + wc * 64 + n * 16 + fq * 4;
;           const uint2 g = *(const uint2*)(G + row * 2048 + col);
;           float v0 = acc[m][n][0] * lo_bf(g.x), v1 = acc[m][n][1] * hi_bf(g.x);
;           float v2 = acc[m][n][2] * lo_bf(g.y), v3 = acc[m][n][3] * hi_bf(g.y);
;           if (pass) {
;             const uint2 pm = *(const uint2*)(mg + row * 2048 + col);
;             v0 += lo_bf(pm.x); v1 += hi_bf(pm.x); v2 += lo_bf(pm.y); v3 += hi_bf(pm.y);
;           }
;           uint2 o; o.x = pack2(v0, v1); o.y = pack2(v2, v3);
;           *(uint2*)(mg + row * 2048 + col) = o;
;         }
	v_lshlrev_b32_e32 v220, 16, v111
	v_and_b32_e32 v221, 0xffff0000, v111
	v_pk_mul_f32 v[218:219], v[48:49], v[218:219]
	v_pk_mul_f32 v[220:221], v[50:51], v[220:221]
	v_lshlrev_b32_e32 v222, 16, v146
	v_and_b32_e32 v223, 0xffff0000, v146
	v_lshlrev_b32_e32 v224, 16, v147
	v_and_b32_e32 v225, 0xffff0000, v147
	v_pk_add_f32 v[218:219], v[218:219], v[222:223]
	v_pk_add_f32 v[220:221], v[220:221], v[224:225]
	v_cvt_pk_bf16_f32 v110, v218, v219
	v_cvt_pk_bf16_f32 v111, v220, v221
	global_store_dwordx2 v226, v[110:111], s[100:101] offset:96
	s_add_u32 s100, s100, 0x10000
	s_addc_u32 s101, s101, 0
	v_lshlrev_b32_e32 v218, 16, v112
	v_and_b32_e32 v219, 0xffff0000, v112
	v_lshlrev_b32_e32 v220, 16, v113
	v_and_b32_e32 v221, 0xffff0000, v113
	v_pk_mul_f32 v[218:219], v[44:45], v[218:219]
	v_pk_mul_f32 v[220:221], v[46:47], v[220:221]
	v_lshlrev_b32_e32 v222, 16, v148
	v_and_b32_e32 v223, 0xffff0000, v148
	v_lshlrev_b32_e32 v224, 16, v149
	v_and_b32_e32 v225, 0xffff0000, v149
	v_pk_add_f32 v[218:219], v[218:219], v[222:223]
	v_pk_add_f32 v[220:221], v[220:221], v[224:225]
	v_cvt_pk_bf16_f32 v112, v218, v219
	v_cvt_pk_bf16_f32 v113, v220, v221
	global_store_dwordx2 v226, v[112:113], s[100:101]
	v_lshlrev_b32_e32 v218, 16, v114
	v_and_b32_e32 v219, 0xffff0000, v114
	v_lshlrev_b32_e32 v220, 16, v115
	v_and_b32_e32 v221, 0xffff0000, v115
	v_pk_mul_f32 v[218:219], v[40:41], v[218:219]
	v_pk_mul_f32 v[220:221], v[42:43], v[220:221]
	v_lshlrev_b32_e32 v222, 16, v150
	v_and_b32_e32 v223, 0xffff0000, v150
	v_lshlrev_b32_e32 v224, 16, v151
	v_and_b32_e32 v225, 0xffff0000, v151
	v_pk_add_f32 v[218:219], v[218:219], v[222:223]
	v_pk_add_f32 v[220:221], v[220:221], v[224:225]
	v_cvt_pk_bf16_f32 v114, v218, v219
	v_cvt_pk_bf16_f32 v115, v220, v221
	global_store_dwordx2 v226, v[114:115], s[100:101] offset:32
	v_lshlrev_b32_e32 v218, 16, v116
	v_and_b32_e32 v219, 0xffff0000, v116
	v_lshlrev_b32_e32 v220, 16, v117
	v_and_b32_e32 v221, 0xffff0000, v117
	v_pk_mul_f32 v[218:219], v[36:37], v[218:219]
	v_pk_mul_f32 v[220:221], v[38:39], v[220:221]
	v_lshlrev_b32_e32 v222, 16, v152
	v_and_b32_e32 v223, 0xffff0000, v152
	v_lshlrev_b32_e32 v224, 16, v153
	v_and_b32_e32 v225, 0xffff0000, v153
	v_pk_add_f32 v[218:219], v[218:219], v[222:223]
	v_pk_add_f32 v[220:221], v[220:221], v[224:225]
	v_cvt_pk_bf16_f32 v116, v218, v219
	v_cvt_pk_bf16_f32 v117, v220, v221
	global_store_dwordx2 v226, v[116:117], s[100:101] offset:64
	v_lshlrev_b32_e32 v218, 16, v118
	v_and_b32_e32 v219, 0xffff0000, v118
	v_lshlrev_b32_e32 v220, 16, v119
	v_and_b32_e32 v221, 0xffff0000, v119
	v_pk_mul_f32 v[218:219], v[32:33], v[218:219]
	v_pk_mul_f32 v[220:221], v[34:35], v[220:221]
	v_lshlrev_b32_e32 v222, 16, v154
	v_and_b32_e32 v223, 0xffff0000, v154
	v_lshlrev_b32_e32 v224, 16, v155
	v_and_b32_e32 v225, 0xffff0000, v155
	v_pk_add_f32 v[218:219], v[218:219], v[222:223]
	v_pk_add_f32 v[220:221], v[220:221], v[224:225]
	v_cvt_pk_bf16_f32 v118, v218, v219
	v_cvt_pk_bf16_f32 v119, v220, v221
	global_store_dwordx2 v226, v[118:119], s[100:101] offset:96
	s_add_u32 s100, s100, 0x10000
	s_addc_u32 s101, s101, 0
	v_lshlrev_b32_e32 v218, 16, v124
	v_and_b32_e32 v219, 0xffff0000, v124
	v_lshlrev_b32_e32 v220, 16, v125
	v_and_b32_e32 v221, 0xffff0000, v125
	v_pk_mul_f32 v[218:219], v[28:29], v[218:219]
	v_pk_mul_f32 v[220:221], v[30:31], v[220:221]
	v_lshlrev_b32_e32 v222, 16, v198
	v_and_b32_e32 v223, 0xffff0000, v198
	v_lshlrev_b32_e32 v224, 16, v199
	v_and_b32_e32 v225, 0xffff0000, v199
	v_pk_add_f32 v[218:219], v[218:219], v[222:223]
	v_pk_add_f32 v[220:221], v[220:221], v[224:225]
	v_cvt_pk_bf16_f32 v124, v218, v219
	v_cvt_pk_bf16_f32 v125, v220, v221
	global_store_dwordx2 v226, v[124:125], s[100:101]
	v_lshlrev_b32_e32 v218, 16, v126
	v_and_b32_e32 v219, 0xffff0000, v126
	v_lshlrev_b32_e32 v220, 16, v127
	v_and_b32_e32 v221, 0xffff0000, v127
	v_pk_mul_f32 v[218:219], v[24:25], v[218:219]
	v_pk_mul_f32 v[220:221], v[26:27], v[220:221]
	v_lshlrev_b32_e32 v222, 16, v200
	v_and_b32_e32 v223, 0xffff0000, v200
	v_lshlrev_b32_e32 v224, 16, v201
	v_and_b32_e32 v225, 0xffff0000, v201
	v_pk_add_f32 v[218:219], v[218:219], v[222:223]
	v_pk_add_f32 v[220:221], v[220:221], v[224:225]
	v_cvt_pk_bf16_f32 v126, v218, v219
	v_cvt_pk_bf16_f32 v127, v220, v221
	global_store_dwordx2 v226, v[126:127], s[100:101] offset:32
	v_lshlrev_b32_e32 v218, 16, v128
	v_and_b32_e32 v219, 0xffff0000, v128
	v_lshlrev_b32_e32 v220, 16, v129
	v_and_b32_e32 v221, 0xffff0000, v129
	v_pk_mul_f32 v[218:219], v[20:21], v[218:219]
	v_pk_mul_f32 v[220:221], v[22:23], v[220:221]
	v_lshlrev_b32_e32 v222, 16, v202
	v_and_b32_e32 v223, 0xffff0000, v202
	v_lshlrev_b32_e32 v224, 16, v203
	v_and_b32_e32 v225, 0xffff0000, v203
	v_pk_add_f32 v[218:219], v[218:219], v[222:223]
	v_pk_add_f32 v[220:221], v[220:221], v[224:225]
	v_cvt_pk_bf16_f32 v128, v218, v219
	v_cvt_pk_bf16_f32 v129, v220, v221
	global_store_dwordx2 v226, v[128:129], s[100:101] offset:64
	v_lshlrev_b32_e32 v218, 16, v130
	v_and_b32_e32 v219, 0xffff0000, v130
	v_lshlrev_b32_e32 v220, 16, v131
	v_and_b32_e32 v221, 0xffff0000, v131
	v_pk_mul_f32 v[218:219], v[16:17], v[218:219]
	v_pk_mul_f32 v[220:221], v[18:19], v[220:221]
	v_lshlrev_b32_e32 v222, 16, v204
	v_and_b32_e32 v223, 0xffff0000, v204
	v_lshlrev_b32_e32 v224, 16, v205
	v_and_b32_e32 v225, 0xffff0000, v205
	v_pk_add_f32 v[218:219], v[218:219], v[222:223]
	v_pk_add_f32 v[220:221], v[220:221], v[224:225]
	v_cvt_pk_bf16_f32 v130, v218, v219
	v_cvt_pk_bf16_f32 v131, v220, v221
	global_store_dwordx2 v226, v[130:131], s[100:101] offset:96
	s_add_u32 s100, s100, 0x10000
	s_addc_u32 s101, s101, 0
	v_lshlrev_b32_e32 v218, 16, v132
; __device__ __forceinline__ float lo_bf(unsigned u) { return __uint_as_float(u << 16); }
; __device__ __forceinline__ float hi_bf(unsigned u) { return __uint_as_float(u & 0xffff0000u); }
; #define ZERO_ACC(acc) _Pragma("unroll") for (int m_ = 0; m_ < 8; ++m_) _Pragma("unroll") for (int n_ = 0; n_ < 4; ++n_) acc[m_][n_] = (f32x4){0.f, 0.f, 0.f, 0.f};
; __device__ __forceinline__ void phase_merge(const Params& p, char* smem) {
;     ...
;   for (int it = 0;; ++it) {
;     int mt, nt;
;     if (!gemm_sched(it, 16, mt, nt)) break;
; #pragma unroll 1
;     for (int pass = 0; pass < 2; ++pass) {
;       const u16* A = (const u16*)(ws + (pass ? OFF_DNQKV : OFF_RH + 64 * MiB));
;       const u16* W = (const u16*)(ws + (pass ? OFF_WPBT : OFF_WPAT));
;       const u16* G = (const u16*)(ws + (pass ? OFF_GB : OFF_GA));
;       f32x4 acc[8][4];
;       ZERO_ACC(acc);
;       gemm_tile_256<false>(A + (size_t)mt * 256 * 1024, 1024, W + (size_t)nt * 128 * 1024, 1024, 1024, smem, acc);
;       int mt2 = mt, nt2 = nt;
;       asm volatile("" : "+s"(mt2), "+s"(nt2));
; #pragma unroll
;       for (int m = 0; m < 8; ++m)
; #pragma unroll
;         for (int n = 0; n < 4; ++n) {
;           const size_t row = (size_t)mt2 * 256 + wr * 128 + m * 16 + fr;
;           const int col = nt2 * 128 + wc * 64 + n * 16 + fq * 4;
;           const uint2 g = *(const uint2*)(G + row * 2048 + col);
;           float v0 = acc[m][n][0] * lo_bf(g.x), v1 = acc[m][n][1] * hi_bf(g.x);
;           float v2 = acc[m][n][2] * lo_bf(g.y), v3 = acc[m][n][3] * hi_bf(g.y);
;           if (pass) {
;             const uint2 pm = *(const uint2*)(mg + row * 2048 + col);
;             v0 += lo_bf(pm.x); v1 += hi_bf(pm.x); v2 += lo_bf(pm.y); v3 += hi_bf(pm.y);
;           }
;           uint2 o; o.x = pack2(v0, v1); o.y = pack2(v2, v3);
;           *(uint2*)(mg + row * 2048 + col) = o;
;         }
	v_and_b32_e32 v219, 0xffff0000, v132
	v_lshlrev_b32_e32 v220, 16, v133
	v_and_b32_e32 v221, 0xffff0000, v133
	v_pk_mul_f32 v[218:219], v[12:13], v[218:219]
	v_pk_mul_f32 v[220:221], v[14:15], v[220:221]
	v_lshlrev_b32_e32 v222, 16, v206
	v_and_b32_e32 v223, 0xffff0000, v206
	v_lshlrev_b32_e32 v224, 16, v207
	v_and_b32_e32 v225, 0xffff0000, v207
	v_pk_add_f32 v[218:219], v[218:219], v[222:223]
	v_pk_add_f32 v[220:221], v[220:221], v[224:225]
	v_cvt_pk_bf16_f32 v132, v218, v219
	v_cvt_pk_bf16_f32 v133, v220, v221
	global_store_dwordx2 v226, v[132:133], s[100:101]
	v_lshlrev_b32_e32 v218, 16, v134
	v_and_b32_e32 v219, 0xffff0000, v134
	v_lshlrev_b32_e32 v220, 16, v135
	v_and_b32_e32 v221, 0xffff0000, v135
	v_pk_mul_f32 v[218:219], v[8:9], v[218:219]
	v_pk_mul_f32 v[220:221], v[10:11], v[220:221]
	v_lshlrev_b32_e32 v222, 16, v208
	v_and_b32_e32 v223, 0xffff0000, v208
	v_lshlrev_b32_e32 v224, 16, v209
	v_and_b32_e32 v225, 0xffff0000, v209
	v_pk_add_f32 v[218:219], v[218:219], v[222:223]
	v_pk_add_f32 v[220:221], v[220:221], v[224:225]
	v_cvt_pk_bf16_f32 v134, v218, v219
	v_cvt_pk_bf16_f32 v135, v220, v221
	global_store_dwordx2 v226, v[134:135], s[100:101] offset:32
	v_lshlrev_b32_e32 v218, 16, v136
	v_and_b32_e32 v219, 0xffff0000, v136
	v_lshlrev_b32_e32 v220, 16, v137
	v_and_b32_e32 v221, 0xffff0000, v137
	v_pk_mul_f32 v[218:219], v[4:5], v[218:219]
	v_pk_mul_f32 v[220:221], v[6:7], v[220:221]
	v_lshlrev_b32_e32 v222, 16, v210
	v_and_b32_e32 v223, 0xffff0000, v210
	v_lshlrev_b32_e32 v224, 16, v211
	v_and_b32_e32 v225, 0xffff0000, v211
	v_pk_add_f32 v[218:219], v[218:219], v[222:223]
	v_pk_add_f32 v[220:221], v[220:221], v[224:225]
	v_cvt_pk_bf16_f32 v136, v218, v219
	v_cvt_pk_bf16_f32 v137, v220, v221
	global_store_dwordx2 v226, v[136:137], s[100:101] offset:64
	v_lshlrev_b32_e32 v218, 16, v138
	v_and_b32_e32 v219, 0xffff0000, v138
	v_lshlrev_b32_e32 v220, 16, v139
	v_and_b32_e32 v221, 0xffff0000, v139
	v_pk_mul_f32 v[218:219], v[0:1], v[218:219]
	v_pk_mul_f32 v[220:221], v[2:3], v[220:221]
	v_lshlrev_b32_e32 v222, 16, v212
	v_and_b32_e32 v223, 0xffff0000, v212
	v_lshlrev_b32_e32 v224, 16, v213
	v_and_b32_e32 v225, 0xffff0000, v213
	v_pk_add_f32 v[218:219], v[218:219], v[222:223]
	v_pk_add_f32 v[220:221], v[220:221], v[224:225]
	v_cvt_pk_bf16_f32 v138, v218, v219
	v_cvt_pk_bf16_f32 v139, v220, v221
	global_store_dwordx2 v226, v[138:139], s[100:101] offset:96
	s_add_i32 s44, s44, s3
	s_add_i32 s14, s14, s3
	s_cmpk_lt_u32 s44, 0x100
	s_cbranch_scc0 .LBB0_1017
	s_branch .LBB0_947
.Lmg_p0:
	s_add_u32 s98, s10, 0x0
	s_addc_u32 s99, s11, 0
	global_load_dwordx2 v[104:105], v226, s[98:99]
	global_load_dwordx2 v[106:107], v226, s[98:99] offset:32
	global_load_dwordx2 v[108:109], v226, s[98:99] offset:64
	global_load_dwordx2 v[110:111], v226, s[98:99] offset:96
	s_add_u32 s98, s98, 0x10000
	s_addc_u32 s99, s99, 0
	global_load_dwordx2 v[112:113], v226, s[98:99]
	global_load_dwordx2 v[114:115], v226, s[98:99] offset:32
	global_load_dwordx2 v[116:117], v226, s[98:99] offset:64
	global_load_dwordx2 v[118:119], v226, s[98:99] offset:96
	s_add_u32 s98, s98, 0x10000
	s_addc_u32 s99, s99, 0
	global_load_dwordx2 v[124:125], v226, s[98:99]
	global_load_dwordx2 v[126:127], v226, s[98:99] offset:32
	global_load_dwordx2 v[128:129], v226, s[98:99] offset:64
	global_load_dwordx2 v[130:131], v226, s[98:99] offset:96
	s_add_u32 s98, s98, 0x10000
	s_addc_u32 s99, s99, 0
	global_load_dwordx2 v[132:133], v226, s[98:99]
	global_load_dwordx2 v[134:135], v226, s[98:99] offset:32
	global_load_dwordx2 v[136:137], v226, s[98:99] offset:64
	global_load_dwordx2 v[138:139], v226, s[98:99] offset:96
	s_waitcnt vmcnt(0)
	s_add_u32 s100, s40, 0x0
	s_addc_u32 s101, s41, 0
	v_lshlrev_b32_e32 v218, 16, v104
	v_and_b32_e32 v219, 0xffff0000, v104
	v_lshlrev_b32_e32 v220, 16, v105
	v_and_b32_e32 v221, 0xffff0000, v105
	v_pk_mul_f32 v[218:219], v[172:173], v[218:219]
	v_pk_mul_f32 v[220:221], v[174:175], v[220:221]
	v_cvt_pk_bf16_f32 v104, v218, v219
	v_cvt_pk_bf16_f32 v105, v220, v221
	global_store_dwordx2 v226, v[104:105], s[100:101]
	v_lshlrev_b32_e32 v218, 16, v106
	v_and_b32_e32 v219, 0xffff0000, v106
	v_lshlrev_b32_e32 v220, 16, v107
	v_and_b32_e32 v221, 0xffff0000, v107
	v_pk_mul_f32 v[218:219], v[168:169], v[218:219]
	v_pk_mul_f32 v[220:221], v[170:171], v[220:221]
	v_cvt_pk_bf16_f32 v106, v218, v219
	v_cvt_pk_bf16_f32 v107, v220, v221
	global_store_dwordx2 v226, v[106:107], s[100:101] offset:32
	v_lshlrev_b32_e32 v218, 16, v108
	v_and_b32_e32 v219, 0xffff0000, v108
	v_lshlrev_b32_e32 v220, 16, v109
	v_and_b32_e32 v221, 0xffff0000, v109
	v_pk_mul_f32 v[218:219], v[164:165], v[218:219]
	v_pk_mul_f32 v[220:221], v[166:167], v[220:221]
	v_cvt_pk_bf16_f32 v108, v218, v219
	v_cvt_pk_bf16_f32 v109, v220, v221
	global_store_dwordx2 v226, v[108:109], s[100:101] offset:64
	v_lshlrev_b32_e32 v218, 16, v110
	v_and_b32_e32 v219, 0xffff0000, v110
	v_lshlrev_b32_e32 v220, 16, v111
	v_and_b32_e32 v221, 0xffff0000, v111
	v_pk_mul_f32 v[218:219], v[160:161], v[218:219]
	v_pk_mul_f32 v[220:221], v[162:163], v[220:221]
	v_cvt_pk_bf16_f32 v110, v218, v219
	v_cvt_pk_bf16_f32 v111, v220, v221
	global_store_dwordx2 v226, v[110:111], s[100:101] offset:96
	s_add_u32 s100, s100, 0x10000
	s_addc_u32 s101, s101, 0
	v_lshlrev_b32_e32 v218, 16, v112
	v_and_b32_e32 v219, 0xffff0000, v112
	v_lshlrev_b32_e32 v220, 16, v113
	v_and_b32_e32 v221, 0xffff0000, v113
	v_pk_mul_f32 v[218:219], v[156:157], v[218:219]
	v_pk_mul_f32 v[220:221], v[158:159], v[220:221]
	v_cvt_pk_bf16_f32 v112, v218, v219
	v_cvt_pk_bf16_f32 v113, v220, v221
	global_store_dwordx2 v226, v[112:113], s[100:101]
	v_lshlrev_b32_e32 v218, 16, v114
; __device__ __forceinline__ float lo_bf(unsigned u) { return __uint_as_float(u << 16); }
; __device__ __forceinline__ float hi_bf(unsigned u) { return __uint_as_float(u & 0xffff0000u); }
; __device__ __forceinline__ void phase_merge(const Params& p, char* smem) {
;     ...
;       for (int m = 0; m < 8; ++m)
; #pragma unroll
;         for (int n = 0; n < 4; ++n) {
;           const size_t row = (size_t)mt2 * 256 + wr * 128 + m * 16 + fr;
;           const int col = nt2 * 128 + wc * 64 + n * 16 + fq * 4;
;           const uint2 g = *(const uint2*)(G + row * 2048 + col);
;           float v0 = acc[m][n][0] * lo_bf(g.x), v1 = acc[m][n][1] * hi_bf(g.x);
;           float v2 = acc[m][n][2] * lo_bf(g.y), v3 = acc[m][n][3] * hi_bf(g.y);
;           if (pass) {
;             const uint2 pm = *(const uint2*)(mg + row * 2048 + col);
;             v0 += lo_bf(pm.x); v1 += hi_bf(pm.x); v2 += lo_bf(pm.y); v3 += hi_bf(pm.y);
;           }
;           uint2 o; o.x = pack2(v0, v1); o.y = pack2(v2, v3);
;           *(uint2*)(mg + row * 2048 + col) = o;
;         }
	v_and_b32_e32 v219, 0xffff0000, v114
	v_lshlrev_b32_e32 v220, 16, v115
	v_and_b32_e32 v221, 0xffff0000, v115
	v_pk_mul_f32 v[218:219], v[120:121], v[218:219]
	v_pk_mul_f32 v[220:221], v[122:123], v[220:221]
	v_cvt_pk_bf16_f32 v114, v218, v219
	v_cvt_pk_bf16_f32 v115, v220, v221
	global_store_dwordx2 v226, v[114:115], s[100:101] offset:32
	v_lshlrev_b32_e32 v218, 16, v116
	v_and_b32_e32 v219, 0xffff0000, v116
	v_lshlrev_b32_e32 v220, 16, v117
	v_and_b32_e32 v221, 0xffff0000, v117
	v_pk_mul_f32 v[218:219], v[100:101], v[218:219]
	v_pk_mul_f32 v[220:221], v[102:103], v[220:221]
	v_cvt_pk_bf16_f32 v116, v218, v219
	v_cvt_pk_bf16_f32 v117, v220, v221
	global_store_dwordx2 v226, v[116:117], s[100:101] offset:64
	v_lshlrev_b32_e32 v218, 16, v118
	v_and_b32_e32 v219, 0xffff0000, v118
	v_lshlrev_b32_e32 v220, 16, v119
	v_and_b32_e32 v221, 0xffff0000, v119
	v_pk_mul_f32 v[218:219], v[96:97], v[218:219]
	v_pk_mul_f32 v[220:221], v[98:99], v[220:221]
	v_cvt_pk_bf16_f32 v118, v218, v219
	v_cvt_pk_bf16_f32 v119, v220, v221
	global_store_dwordx2 v226, v[118:119], s[100:101] offset:96
	s_add_u32 s100, s100, 0x10000
	s_addc_u32 s101, s101, 0
	v_lshlrev_b32_e32 v218, 16, v124
	v_and_b32_e32 v219, 0xffff0000, v124
	v_lshlrev_b32_e32 v220, 16, v125
	v_and_b32_e32 v221, 0xffff0000, v125
	v_pk_mul_f32 v[218:219], v[92:93], v[218:219]
	v_pk_mul_f32 v[220:221], v[94:95], v[220:221]
	v_cvt_pk_bf16_f32 v124, v218, v219
	v_cvt_pk_bf16_f32 v125, v220, v221
	global_store_dwordx2 v226, v[124:125], s[100:101]
	v_lshlrev_b32_e32 v218, 16, v126
	v_and_b32_e32 v219, 0xffff0000, v126
	v_lshlrev_b32_e32 v220, 16, v127
	v_and_b32_e32 v221, 0xffff0000, v127
	v_pk_mul_f32 v[218:219], v[88:89], v[218:219]
	v_pk_mul_f32 v[220:221], v[90:91], v[220:221]
	v_cvt_pk_bf16_f32 v126, v218, v219
	v_cvt_pk_bf16_f32 v127, v220, v221
	global_store_dwordx2 v226, v[126:127], s[100:101] offset:32
	v_lshlrev_b32_e32 v218, 16, v128
	v_and_b32_e32 v219, 0xffff0000, v128
	v_lshlrev_b32_e32 v220, 16, v129
	v_and_b32_e32 v221, 0xffff0000, v129
	v_pk_mul_f32 v[218:219], v[84:85], v[218:219]
	v_pk_mul_f32 v[220:221], v[86:87], v[220:221]
	v_cvt_pk_bf16_f32 v128, v218, v219
	v_cvt_pk_bf16_f32 v129, v220, v221
	global_store_dwordx2 v226, v[128:129], s[100:101] offset:64
	v_lshlrev_b32_e32 v218, 16, v130
	v_and_b32_e32 v219, 0xffff0000, v130
	v_lshlrev_b32_e32 v220, 16, v131
	v_and_b32_e32 v221, 0xffff0000, v131
	v_pk_mul_f32 v[218:219], v[80:81], v[218:219]
	v_pk_mul_f32 v[220:221], v[82:83], v[220:221]
	v_cvt_pk_bf16_f32 v130, v218, v219
	v_cvt_pk_bf16_f32 v131, v220, v221
	global_store_dwordx2 v226, v[130:131], s[100:101] offset:96
	s_add_u32 s100, s100, 0x10000
	s_addc_u32 s101, s101, 0
	v_lshlrev_b32_e32 v218, 16, v132
	v_and_b32_e32 v219, 0xffff0000, v132
	v_lshlrev_b32_e32 v220, 16, v133
	v_and_b32_e32 v221, 0xffff0000, v133
	v_pk_mul_f32 v[218:219], v[76:77], v[218:219]
	v_pk_mul_f32 v[220:221], v[78:79], v[220:221]
	v_cvt_pk_bf16_f32 v132, v218, v219
	v_cvt_pk_bf16_f32 v133, v220, v221
	global_store_dwordx2 v226, v[132:133], s[100:101]
	v_lshlrev_b32_e32 v218, 16, v134
	v_and_b32_e32 v219, 0xffff0000, v134
	v_lshlrev_b32_e32 v220, 16, v135
	v_and_b32_e32 v221, 0xffff0000, v135
	v_pk_mul_f32 v[218:219], v[72:73], v[218:219]
	v_pk_mul_f32 v[220:221], v[74:75], v[220:221]
	v_cvt_pk_bf16_f32 v134, v218, v219
	v_cvt_pk_bf16_f32 v135, v220, v221
	global_store_dwordx2 v226, v[134:135], s[100:101] offset:32
	v_lshlrev_b32_e32 v218, 16, v136
	v_and_b32_e32 v219, 0xffff0000, v136
	v_lshlrev_b32_e32 v220, 16, v137
	v_and_b32_e32 v221, 0xffff0000, v137
	v_pk_mul_f32 v[218:219], v[68:69], v[218:219]
	v_pk_mul_f32 v[220:221], v[70:71], v[220:221]
	v_cvt_pk_bf16_f32 v136, v218, v219
	v_cvt_pk_bf16_f32 v137, v220, v221
	global_store_dwordx2 v226, v[136:137], s[100:101] offset:64
	v_lshlrev_b32_e32 v218, 16, v138
	v_and_b32_e32 v219, 0xffff0000, v138
	v_lshlrev_b32_e32 v220, 16, v139
	v_and_b32_e32 v221, 0xffff0000, v139
	v_pk_mul_f32 v[218:219], v[64:65], v[218:219]
	v_pk_mul_f32 v[220:221], v[66:67], v[220:221]
	v_cvt_pk_bf16_f32 v138, v218, v219
	v_cvt_pk_bf16_f32 v139, v220, v221
	global_store_dwordx2 v226, v[138:139], s[100:101] offset:96
	s_add_u32 s98, s10, 0x40000
	s_addc_u32 s99, s11, 0
	global_load_dwordx2 v[104:105], v226, s[98:99]
	global_load_dwordx2 v[106:107], v226, s[98:99] offset:32
	global_load_dwordx2 v[108:109], v226, s[98:99] offset:64
	global_load_dwordx2 v[110:111], v226, s[98:99] offset:96
	s_add_u32 s98, s98, 0x10000
	s_addc_u32 s99, s99, 0
	global_load_dwordx2 v[112:113], v226, s[98:99]
	global_load_dwordx2 v[114:115], v226, s[98:99] offset:32
	global_load_dwordx2 v[116:117], v226, s[98:99] offset:64
	global_load_dwordx2 v[118:119], v226, s[98:99] offset:96
	s_add_u32 s98, s98, 0x10000
	s_addc_u32 s99, s99, 0
	global_load_dwordx2 v[124:125], v226, s[98:99]
	global_load_dwordx2 v[126:127], v226, s[98:99] offset:32
	global_load_dwordx2 v[128:129], v226, s[98:99] offset:64
	global_load_dwordx2 v[130:131], v226, s[98:99] offset:96
	s_add_u32 s98, s98, 0x10000
	s_addc_u32 s99, s99, 0
	global_load_dwordx2 v[132:133], v226, s[98:99]
	global_load_dwordx2 v[134:135], v226, s[98:99] offset:32
	global_load_dwordx2 v[136:137], v226, s[98:99] offset:64
	global_load_dwordx2 v[138:139], v226, s[98:99] offset:96
	s_waitcnt vmcnt(0)
; __device__ __forceinline__ float lo_bf(unsigned u) { return __uint_as_float(u << 16); }
; __device__ __forceinline__ float hi_bf(unsigned u) { return __uint_as_float(u & 0xffff0000u); }
; __device__ __forceinline__ void phase_merge(const Params& p, char* smem) {
;     ...
;       for (int m = 0; m < 8; ++m)
; #pragma unroll
;         for (int n = 0; n < 4; ++n) {
;           const size_t row = (size_t)mt2 * 256 + wr * 128 + m * 16 + fr;
;           const int col = nt2 * 128 + wc * 64 + n * 16 + fq * 4;
;           const uint2 g = *(const uint2*)(G + row * 2048 + col);
;           float v0 = acc[m][n][0] * lo_bf(g.x), v1 = acc[m][n][1] * hi_bf(g.x);
;           float v2 = acc[m][n][2] * lo_bf(g.y), v3 = acc[m][n][3] * hi_bf(g.y);
;           if (pass) {
;             const uint2 pm = *(const uint2*)(mg + row * 2048 + col);
;             v0 += lo_bf(pm.x); v1 += hi_bf(pm.x); v2 += lo_bf(pm.y); v3 += hi_bf(pm.y);
;           }
;           uint2 o; o.x = pack2(v0, v1); o.y = pack2(v2, v3);
;           *(uint2*)(mg + row * 2048 + col) = o;
;         }
	s_add_u32 s100, s40, 0x40000
	s_addc_u32 s101, s41, 0
	v_lshlrev_b32_e32 v218, 16, v104
	v_and_b32_e32 v219, 0xffff0000, v104
	v_lshlrev_b32_e32 v220, 16, v105
	v_and_b32_e32 v221, 0xffff0000, v105
	v_pk_mul_f32 v[218:219], v[60:61], v[218:219]
	v_pk_mul_f32 v[220:221], v[62:63], v[220:221]
	v_cvt_pk_bf16_f32 v104, v218, v219
	v_cvt_pk_bf16_f32 v105, v220, v221
	global_store_dwordx2 v226, v[104:105], s[100:101]
	v_lshlrev_b32_e32 v218, 16, v106
	v_and_b32_e32 v219, 0xffff0000, v106
	v_lshlrev_b32_e32 v220, 16, v107
	v_and_b32_e32 v221, 0xffff0000, v107
	v_pk_mul_f32 v[218:219], v[56:57], v[218:219]
	v_pk_mul_f32 v[220:221], v[58:59], v[220:221]
	v_cvt_pk_bf16_f32 v106, v218, v219
	v_cvt_pk_bf16_f32 v107, v220, v221
	global_store_dwordx2 v226, v[106:107], s[100:101] offset:32
	v_lshlrev_b32_e32 v218, 16, v108
	v_and_b32_e32 v219, 0xffff0000, v108
	v_lshlrev_b32_e32 v220, 16, v109
	v_and_b32_e32 v221, 0xffff0000, v109
	v_pk_mul_f32 v[218:219], v[52:53], v[218:219]
	v_pk_mul_f32 v[220:221], v[54:55], v[220:221]
	v_cvt_pk_bf16_f32 v108, v218, v219
	v_cvt_pk_bf16_f32 v109, v220, v221
	global_store_dwordx2 v226, v[108:109], s[100:101] offset:64
	v_lshlrev_b32_e32 v218, 16, v110
	v_and_b32_e32 v219, 0xffff0000, v110
	v_lshlrev_b32_e32 v220, 16, v111
	v_and_b32_e32 v221, 0xffff0000, v111
	v_pk_mul_f32 v[218:219], v[48:49], v[218:219]
	v_pk_mul_f32 v[220:221], v[50:51], v[220:221]
	v_cvt_pk_bf16_f32 v110, v218, v219
	v_cvt_pk_bf16_f32 v111, v220, v221
	global_store_dwordx2 v226, v[110:111], s[100:101] offset:96
	s_add_u32 s100, s100, 0x10000
	s_addc_u32 s101, s101, 0
	v_lshlrev_b32_e32 v218, 16, v112
	v_and_b32_e32 v219, 0xffff0000, v112
	v_lshlrev_b32_e32 v220, 16, v113
	v_and_b32_e32 v221, 0xffff0000, v113
	v_pk_mul_f32 v[218:219], v[44:45], v[218:219]
	v_pk_mul_f32 v[220:221], v[46:47], v[220:221]
	v_cvt_pk_bf16_f32 v112, v218, v219
	v_cvt_pk_bf16_f32 v113, v220, v221
	global_store_dwordx2 v226, v[112:113], s[100:101]
	v_lshlrev_b32_e32 v218, 16, v114
	v_and_b32_e32 v219, 0xffff0000, v114
	v_lshlrev_b32_e32 v220, 16, v115
	v_and_b32_e32 v221, 0xffff0000, v115
	v_pk_mul_f32 v[218:219], v[40:41], v[218:219]
	v_pk_mul_f32 v[220:221], v[42:43], v[220:221]
	v_cvt_pk_bf16_f32 v114, v218, v219
	v_cvt_pk_bf16_f32 v115, v220, v221
	global_store_dwordx2 v226, v[114:115], s[100:101] offset:32
	v_lshlrev_b32_e32 v218, 16, v116
	v_and_b32_e32 v219, 0xffff0000, v116
	v_lshlrev_b32_e32 v220, 16, v117
	v_and_b32_e32 v221, 0xffff0000, v117
	v_pk_mul_f32 v[218:219], v[36:37], v[218:219]
	v_pk_mul_f32 v[220:221], v[38:39], v[220:221]
	v_cvt_pk_bf16_f32 v116, v218, v219
	v_cvt_pk_bf16_f32 v117, v220, v221
	global_store_dwordx2 v226, v[116:117], s[100:101] offset:64
	v_lshlrev_b32_e32 v218, 16, v118
	v_and_b32_e32 v219, 0xffff0000, v118
	v_lshlrev_b32_e32 v220, 16, v119
	v_and_b32_e32 v221, 0xffff0000, v119
	v_pk_mul_f32 v[218:219], v[32:33], v[218:219]
	v_pk_mul_f32 v[220:221], v[34:35], v[220:221]
	v_cvt_pk_bf16_f32 v118, v218, v219
	v_cvt_pk_bf16_f32 v119, v220, v221
	global_store_dwordx2 v226, v[118:119], s[100:101] offset:96
	s_add_u32 s100, s100, 0x10000
	s_addc_u32 s101, s101, 0
	v_lshlrev_b32_e32 v218, 16, v124
	v_and_b32_e32 v219, 0xffff0000, v124
	v_lshlrev_b32_e32 v220, 16, v125
	v_and_b32_e32 v221, 0xffff0000, v125
	v_pk_mul_f32 v[218:219], v[28:29], v[218:219]
	v_pk_mul_f32 v[220:221], v[30:31], v[220:221]
	v_cvt_pk_bf16_f32 v124, v218, v219
	v_cvt_pk_bf16_f32 v125, v220, v221
	global_store_dwordx2 v226, v[124:125], s[100:101]
	v_lshlrev_b32_e32 v218, 16, v126
	v_and_b32_e32 v219, 0xffff0000, v126
	v_lshlrev_b32_e32 v220, 16, v127
	v_and_b32_e32 v221, 0xffff0000, v127
	v_pk_mul_f32 v[218:219], v[24:25], v[218:219]
	v_pk_mul_f32 v[220:221], v[26:27], v[220:221]
	v_cvt_pk_bf16_f32 v126, v218, v219
	v_cvt_pk_bf16_f32 v127, v220, v221
	global_store_dwordx2 v226, v[126:127], s[100:101] offset:32
	v_lshlrev_b32_e32 v218, 16, v128
	v_and_b32_e32 v219, 0xffff0000, v128
	v_lshlrev_b32_e32 v220, 16, v129
	v_and_b32_e32 v221, 0xffff0000, v129
	v_pk_mul_f32 v[218:219], v[20:21], v[218:219]
	v_pk_mul_f32 v[220:221], v[22:23], v[220:221]
	v_cvt_pk_bf16_f32 v128, v218, v219
	v_cvt_pk_bf16_f32 v129, v220, v221
	global_store_dwordx2 v226, v[128:129], s[100:101] offset:64
	v_lshlrev_b32_e32 v218, 16, v130
	v_and_b32_e32 v219, 0xffff0000, v130
	v_lshlrev_b32_e32 v220, 16, v131
	v_and_b32_e32 v221, 0xffff0000, v131
	v_pk_mul_f32 v[218:219], v[16:17], v[218:219]
	v_pk_mul_f32 v[220:221], v[18:19], v[220:221]
	v_cvt_pk_bf16_f32 v130, v218, v219
	v_cvt_pk_bf16_f32 v131, v220, v221
	global_store_dwordx2 v226, v[130:131], s[100:101] offset:96
	s_add_u32 s100, s100, 0x10000
	s_addc_u32 s101, s101, 0
	v_lshlrev_b32_e32 v218, 16, v132
	v_and_b32_e32 v219, 0xffff0000, v132
	v_lshlrev_b32_e32 v220, 16, v133
	v_and_b32_e32 v221, 0xffff0000, v133
	v_pk_mul_f32 v[218:219], v[12:13], v[218:219]
	v_pk_mul_f32 v[220:221], v[14:15], v[220:221]
	v_cvt_pk_bf16_f32 v132, v218, v219
	v_cvt_pk_bf16_f32 v133, v220, v221
	global_store_dwordx2 v226, v[132:133], s[100:101]
	v_lshlrev_b32_e32 v218, 16, v134
	v_and_b32_e32 v219, 0xffff0000, v134
	v_lshlrev_b32_e32 v220, 16, v135
	v_and_b32_e32 v221, 0xffff0000, v135
	v_pk_mul_f32 v[218:219], v[8:9], v[218:219]
	v_pk_mul_f32 v[220:221], v[10:11], v[220:221]
	v_cvt_pk_bf16_f32 v134, v218, v219
	v_cvt_pk_bf16_f32 v135, v220, v221
	global_store_dwordx2 v226, v[134:135], s[100:101] offset:32
	v_lshlrev_b32_e32 v218, 16, v136
	v_and_b32_e32 v219, 0xffff0000, v136
	v_lshlrev_b32_e32 v220, 16, v137
	v_and_b32_e32 v221, 0xffff0000, v137
	v_pk_mul_f32 v[218:219], v[4:5], v[218:219]
	v_pk_mul_f32 v[220:221], v[6:7], v[220:221]
	v_cvt_pk_bf16_f32 v136, v218, v219
	v_cvt_pk_bf16_f32 v137, v220, v221
	global_store_dwordx2 v226, v[136:137], s[100:101] offset:64
	v_lshlrev_b32_e32 v218, 16, v138
	v_and_b32_e32 v219, 0xffff0000, v138
	v_lshlrev_b32_e32 v220, 16, v139
	v_and_b32_e32 v221, 0xffff0000, v139
	v_pk_mul_f32 v[218:219], v[0:1], v[218:219]
	v_pk_mul_f32 v[220:221], v[2:3], v[220:221]
	v_cvt_pk_bf16_f32 v138, v218, v219
	v_cvt_pk_bf16_f32 v139, v220, v221
	global_store_dwordx2 v226, v[138:139], s[100:101] offset:96
	s_mov_b64 s[6:7], 0
	s_branch .LBB0_948

; __device__ __forceinline__ void phase_outproj(const Params& p, char* smem) {
;     ...
;     const int b = (mt * 256) >> 14;
; #pragma unroll
;     for (int n = 0; n < 4; ++n) {
;       const int col = nt * 128 + wc * 64 + n * 16 + fq * 4;
;       const float4 g1 = *(const float4*)(mod + b * 12288 + 4096 + col);
; #pragma unroll
;       for (int m = 0; m < 8; ++m) {
;         const size_t row = (size_t)mt * 256 + wr * 128 + m * 16 + fr;
;         const float4 xv = *(const float4*)(p.x + row * D + col);
;         float4 o;
;         o.x = ALPHA * xv.x + (1.f + g1.x) * acc[m][n][0];
;         o.y = ALPHA * xv.y + (1.f + g1.y) * acc[m][n][1];
;         o.z = ALPHA * xv.z + (1.f + g1.z) * acc[m][n][2];
;         o.w = ALPHA * xv.w + (1.f + g1.w) * acc[m][n][3];
;         *(float4*)(p.out + row * D + col) = o;
;       }
;     }
.LBB0_1030:
	s_lshl_b32 s0, s21, 19
	v_readlane_b32 s64, v253, 16
	v_readlane_b32 s65, v253, 17
	s_waitcnt vmcnt(0)
	v_lshl_add_u64 v[92:93], s[0:1], 0, v[176:177]
	v_lshl_or_b32 v178, s24, 9, v192
	v_lshlrev_b32_e32 v132, 2, v92
	v_add_u32_e32 v132, v132, v178
	s_mov_b64 s[8:9], s[64:65]
	s_barrier
	global_load_dwordx4 v[92:95], v178, s[4:5]
	global_load_dwordx4 v[96:99], v178, s[4:5] offset:64
	global_load_dwordx4 v[148:151], v178, s[4:5] offset:128
	global_load_dwordx4 v[136:139], v178, s[4:5] offset:192
	s_mov_b64 s[98:99], s[8:9]
	global_load_dwordx4 v[104:107], v132, s[98:99]
	global_load_dwordx4 v[108:111], v132, s[98:99] offset:64
	s_add_u32 s98, s98, 0x20000
	s_addc_u32 s99, s99, 0
	global_load_dwordx4 v[112:115], v132, s[98:99]
	global_load_dwordx4 v[116:119], v132, s[98:99] offset:64
	s_add_u32 s98, s98, 0x20000
	s_addc_u32 s99, s99, 0
	global_load_dwordx4 v[120:123], v132, s[98:99]
	global_load_dwordx4 v[124:127], v132, s[98:99] offset:64
	s_add_u32 s98, s98, 0x20000
	s_addc_u32 s99, s99, 0
	global_load_dwordx4 v[128:131], v132, s[98:99]
	global_load_dwordx4 v[198:201], v132, s[98:99] offset:64
	s_add_u32 s98, s98, 0x20000
	s_addc_u32 s99, s99, 0
	global_load_dwordx4 v[202:205], v132, s[98:99]
	global_load_dwordx4 v[206:209], v132, s[98:99] offset:64
	s_add_u32 s98, s98, 0x20000
	s_addc_u32 s99, s99, 0
	global_load_dwordx4 v[210:213], v132, s[98:99]
	global_load_dwordx4 v[220:223], v132, s[98:99] offset:64
	s_add_u32 s98, s98, 0x20000
	s_addc_u32 s99, s99, 0
	global_load_dwordx4 v[224:227], v132, s[98:99]
	global_load_dwordx4 v[228:231], v132, s[98:99] offset:64
	s_add_u32 s98, s98, 0x20000
	s_addc_u32 s99, s99, 0
	global_load_dwordx4 v[232:235], v132, s[98:99]
	global_load_dwordx4 v[236:239], v132, s[98:99] offset:64
	s_waitcnt vmcnt(0)
	v_pk_add_f32 v[92:93], v[92:93], 1.0 op_sel_hi:[1,0]
	v_pk_add_f32 v[94:95], v[94:95], 1.0 op_sel_hi:[1,0]
	v_pk_add_f32 v[96:97], v[96:97], 1.0 op_sel_hi:[1,0]
	v_pk_add_f32 v[98:99], v[98:99], 1.0 op_sel_hi:[1,0]
	v_pk_add_f32 v[148:149], v[148:149], 1.0 op_sel_hi:[1,0]
	v_pk_add_f32 v[150:151], v[150:151], 1.0 op_sel_hi:[1,0]
	v_pk_add_f32 v[136:137], v[136:137], 1.0 op_sel_hi:[1,0]
	v_pk_add_f32 v[138:139], v[138:139], 1.0 op_sel_hi:[1,0]
	s_mov_b64 s[100:101], s[52:53]
	v_pk_mul_f32 v[104:105], v[104:105], s[6:7] op_sel_hi:[1,0]
	v_pk_mul_f32 v[106:107], v[106:107], s[6:7] op_sel_hi:[1,0]
	v_pk_fma_f32 v[104:105], v[172:173], v[92:93], v[104:105]
	v_pk_fma_f32 v[106:107], v[174:175], v[94:95], v[106:107]
	v_pk_mul_f32 v[108:109], v[108:109], s[6:7] op_sel_hi:[1,0]
	v_pk_mul_f32 v[110:111], v[110:111], s[6:7] op_sel_hi:[1,0]
	v_pk_fma_f32 v[108:109], v[152:153], v[96:97], v[108:109]
	v_pk_fma_f32 v[110:111], v[154:155], v[98:99], v[110:111]
	global_store_dwordx4 v132, v[104:107], s[100:101]
	global_store_dwordx4 v132, v[108:111], s[100:101] offset:64
	s_add_u32 s100, s100, 0x20000
	s_addc_u32 s101, s101, 0
	v_pk_mul_f32 v[112:113], v[112:113], s[6:7] op_sel_hi:[1,0]
	v_pk_mul_f32 v[114:115], v[114:115], s[6:7] op_sel_hi:[1,0]
	v_pk_fma_f32 v[112:113], v[168:169], v[92:93], v[112:113]
	v_pk_fma_f32 v[114:115], v[170:171], v[94:95], v[114:115]
	v_pk_mul_f32 v[116:117], v[116:117], s[6:7] op_sel_hi:[1,0]
	v_pk_mul_f32 v[118:119], v[118:119], s[6:7] op_sel_hi:[1,0]
	v_pk_fma_f32 v[116:117], v[140:141], v[96:97], v[116:117]
	v_pk_fma_f32 v[118:119], v[142:143], v[98:99], v[118:119]
	global_store_dwordx4 v132, v[112:115], s[100:101]
	global_store_dwordx4 v132, v[116:119], s[100:101] offset:64
	s_add_u32 s100, s100, 0x20000
	s_addc_u32 s101, s101, 0
	v_pk_mul_f32 v[120:121], v[120:121], s[6:7] op_sel_hi:[1,0]
	v_pk_mul_f32 v[122:123], v[122:123], s[6:7] op_sel_hi:[1,0]
	v_pk_fma_f32 v[120:121], v[164:165], v[92:93], v[120:121]
	v_pk_fma_f32 v[122:123], v[166:167], v[94:95], v[122:123]
	v_pk_mul_f32 v[124:125], v[124:125], s[6:7] op_sel_hi:[1,0]
	v_pk_mul_f32 v[126:127], v[126:127], s[6:7] op_sel_hi:[1,0]
	v_pk_fma_f32 v[124:125], v[88:89], v[96:97], v[124:125]
	v_pk_fma_f32 v[126:127], v[90:91], v[98:99], v[126:127]
	global_store_dwordx4 v132, v[120:123], s[100:101]
	global_store_dwordx4 v132, v[124:127], s[100:101] offset:64
	s_add_u32 s100, s100, 0x20000
	s_addc_u32 s101, s101, 0
	v_pk_mul_f32 v[128:129], v[128:129], s[6:7] op_sel_hi:[1,0]
	v_pk_mul_f32 v[130:131], v[130:131], s[6:7] op_sel_hi:[1,0]
	v_pk_fma_f32 v[128:129], v[160:161], v[92:93], v[128:129]
	v_pk_fma_f32 v[130:131], v[162:163], v[94:95], v[130:131]
	v_pk_mul_f32 v[198:199], v[198:199], s[6:7] op_sel_hi:[1,0]
	v_pk_mul_f32 v[200:201], v[200:201], s[6:7] op_sel_hi:[1,0]
	v_pk_fma_f32 v[198:199], v[80:81], v[96:97], v[198:199]
	v_pk_fma_f32 v[200:201], v[82:83], v[98:99], v[200:201]
	global_store_dwordx4 v132, v[128:131], s[100:101]
	global_store_dwordx4 v132, v[198:201], s[100:101] offset:64
	s_add_u32 s100, s100, 0x20000
	s_addc_u32 s101, s101, 0
	v_pk_mul_f32 v[202:203], v[202:203], s[6:7] op_sel_hi:[1,0]
	v_pk_mul_f32 v[204:205], v[204:205], s[6:7] op_sel_hi:[1,0]
	v_pk_fma_f32 v[202:203], v[156:157], v[92:93], v[202:203]
	v_pk_fma_f32 v[204:205], v[158:159], v[94:95], v[204:205]
	v_pk_mul_f32 v[206:207], v[206:207], s[6:7] op_sel_hi:[1,0]
	v_pk_mul_f32 v[208:209], v[208:209], s[6:7] op_sel_hi:[1,0]
	v_pk_fma_f32 v[206:207], v[76:77], v[96:97], v[206:207]
	v_pk_fma_f32 v[208:209], v[78:79], v[98:99], v[208:209]
	global_store_dwordx4 v132, v[202:205], s[100:101]
	global_store_dwordx4 v132, v[206:209], s[100:101] offset:64
	s_add_u32 s100, s100, 0x20000
	s_addc_u32 s101, s101, 0
	v_pk_mul_f32 v[210:211], v[210:211], s[6:7] op_sel_hi:[1,0]
	v_pk_mul_f32 v[212:213], v[212:213], s[6:7] op_sel_hi:[1,0]
; __device__ __forceinline__ void phase_outproj(const Params& p, char* smem) {
;     ...
;     const int b = (mt * 256) >> 14;
; #pragma unroll
;     for (int n = 0; n < 4; ++n) {
;       const int col = nt * 128 + wc * 64 + n * 16 + fq * 4;
;       const float4 g1 = *(const float4*)(mod + b * 12288 + 4096 + col);
; #pragma unroll
;       for (int m = 0; m < 8; ++m) {
;         const size_t row = (size_t)mt * 256 + wr * 128 + m * 16 + fr;
;         const float4 xv = *(const float4*)(p.x + row * D + col);
;         float4 o;
;         o.x = ALPHA * xv.x + (1.f + g1.x) * acc[m][n][0];
;         o.y = ALPHA * xv.y + (1.f + g1.y) * acc[m][n][1];
;         o.z = ALPHA * xv.z + (1.f + g1.z) * acc[m][n][2];
;         o.w = ALPHA * xv.w + (1.f + g1.w) * acc[m][n][3];
;         *(float4*)(p.out + row * D + col) = o;
;       }
;     }
	v_pk_fma_f32 v[210:211], v[144:145], v[92:93], v[210:211]
	v_pk_fma_f32 v[212:213], v[146:147], v[94:95], v[212:213]
	v_pk_mul_f32 v[220:221], v[220:221], s[6:7] op_sel_hi:[1,0]
	v_pk_mul_f32 v[222:223], v[222:223], s[6:7] op_sel_hi:[1,0]
	v_pk_fma_f32 v[220:221], v[68:69], v[96:97], v[220:221]
	v_pk_fma_f32 v[222:223], v[70:71], v[98:99], v[222:223]
	global_store_dwordx4 v132, v[210:213], s[100:101]
	global_store_dwordx4 v132, v[220:223], s[100:101] offset:64
	s_add_u32 s100, s100, 0x20000
	s_addc_u32 s101, s101, 0
	v_pk_mul_f32 v[224:225], v[224:225], s[6:7] op_sel_hi:[1,0]
	v_pk_mul_f32 v[226:227], v[226:227], s[6:7] op_sel_hi:[1,0]
	v_pk_fma_f32 v[224:225], v[100:101], v[92:93], v[224:225]
	v_pk_fma_f32 v[226:227], v[102:103], v[94:95], v[226:227]
	v_pk_mul_f32 v[228:229], v[228:229], s[6:7] op_sel_hi:[1,0]
	v_pk_mul_f32 v[230:231], v[230:231], s[6:7] op_sel_hi:[1,0]
	v_pk_fma_f32 v[228:229], v[60:61], v[96:97], v[228:229]
	v_pk_fma_f32 v[230:231], v[62:63], v[98:99], v[230:231]
	global_store_dwordx4 v132, v[224:227], s[100:101]
	global_store_dwordx4 v132, v[228:231], s[100:101] offset:64
	s_add_u32 s100, s100, 0x20000
	s_addc_u32 s101, s101, 0
	v_pk_mul_f32 v[232:233], v[232:233], s[6:7] op_sel_hi:[1,0]
	v_pk_mul_f32 v[234:235], v[234:235], s[6:7] op_sel_hi:[1,0]
	v_pk_fma_f32 v[232:233], v[84:85], v[92:93], v[232:233]
	v_pk_fma_f32 v[234:235], v[86:87], v[94:95], v[234:235]
	v_pk_mul_f32 v[236:237], v[236:237], s[6:7] op_sel_hi:[1,0]
	v_pk_mul_f32 v[238:239], v[238:239], s[6:7] op_sel_hi:[1,0]
	v_pk_fma_f32 v[236:237], v[52:53], v[96:97], v[236:237]
	v_pk_fma_f32 v[238:239], v[54:55], v[98:99], v[238:239]
	global_store_dwordx4 v132, v[232:235], s[100:101]
	global_store_dwordx4 v132, v[236:239], s[100:101] offset:64
	s_mov_b64 s[98:99], s[8:9]
	global_load_dwordx4 v[104:107], v132, s[98:99] offset:128
	global_load_dwordx4 v[108:111], v132, s[98:99] offset:192
	s_add_u32 s98, s98, 0x20000
	s_addc_u32 s99, s99, 0
	global_load_dwordx4 v[112:115], v132, s[98:99] offset:128
	global_load_dwordx4 v[116:119], v132, s[98:99] offset:192
	s_add_u32 s98, s98, 0x20000
	s_addc_u32 s99, s99, 0
	global_load_dwordx4 v[120:123], v132, s[98:99] offset:128
	global_load_dwordx4 v[124:127], v132, s[98:99] offset:192
	s_add_u32 s98, s98, 0x20000
	s_addc_u32 s99, s99, 0
	global_load_dwordx4 v[128:131], v132, s[98:99] offset:128
	global_load_dwordx4 v[198:201], v132, s[98:99] offset:192
	s_add_u32 s98, s98, 0x20000
	s_addc_u32 s99, s99, 0
	global_load_dwordx4 v[202:205], v132, s[98:99] offset:128
	global_load_dwordx4 v[206:209], v132, s[98:99] offset:192
	s_add_u32 s98, s98, 0x20000
	s_addc_u32 s99, s99, 0
	global_load_dwordx4 v[210:213], v132, s[98:99] offset:128
	global_load_dwordx4 v[220:223], v132, s[98:99] offset:192
	s_add_u32 s98, s98, 0x20000
	s_addc_u32 s99, s99, 0
	global_load_dwordx4 v[224:227], v132, s[98:99] offset:128
	global_load_dwordx4 v[228:231], v132, s[98:99] offset:192
	s_add_u32 s98, s98, 0x20000
	s_addc_u32 s99, s99, 0
	global_load_dwordx4 v[232:235], v132, s[98:99] offset:128
	global_load_dwordx4 v[236:239], v132, s[98:99] offset:192
	s_waitcnt vmcnt(0)
; #define ZERO_ACC(acc) _Pragma("unroll") for (int m_ = 0; m_ < 8; ++m_) _Pragma("unroll") for (int n_ = 0; n_ < 4; ++n_) acc[m_][n_] = (f32x4){0.f, 0.f, 0.f, 0.f};
; __device__ __forceinline__ void phase_outproj(const Params& p, char* smem) {
;     ...
;   for (int it = 0;; ++it) {
;     int mt, nt;
;     if (!gemm_sched(it, 16, mt, nt)) break;
;     f32x4 acc[8][4];
;     ZERO_ACC(acc);
;     gemm_tile_256<false>(mg + (size_t)mt * 256 * D, D, wo + (size_t)nt * 128 * D, D, D, smem, acc);
;     const int b = (mt * 256) >> 14;
; #pragma unroll
;     for (int n = 0; n < 4; ++n) {
;       const int col = nt * 128 + wc * 64 + n * 16 + fq * 4;
;       const float4 g1 = *(const float4*)(mod + b * 12288 + 4096 + col);
; #pragma unroll
;       for (int m = 0; m < 8; ++m) {
;         const size_t row = (size_t)mt * 256 + wr * 128 + m * 16 + fr;
;         const float4 xv = *(const float4*)(p.x + row * D + col);
;         float4 o;
;         o.x = ALPHA * xv.x + (1.f + g1.x) * acc[m][n][0];
;         o.y = ALPHA * xv.y + (1.f + g1.y) * acc[m][n][1];
;         o.z = ALPHA * xv.z + (1.f + g1.z) * acc[m][n][2];
;         o.w = ALPHA * xv.w + (1.f + g1.w) * acc[m][n][3];
;         *(float4*)(p.out + row * D + col) = o;
;       }
;     }
	s_mov_b64 s[100:101], s[52:53]
	v_pk_mul_f32 v[104:105], v[104:105], s[6:7] op_sel_hi:[1,0]
	v_pk_mul_f32 v[106:107], v[106:107], s[6:7] op_sel_hi:[1,0]
	v_pk_fma_f32 v[104:105], v[72:73], v[148:149], v[104:105]
	v_pk_fma_f32 v[106:107], v[74:75], v[150:151], v[106:107]
	v_pk_mul_f32 v[108:109], v[108:109], s[6:7] op_sel_hi:[1,0]
	v_pk_mul_f32 v[110:111], v[110:111], s[6:7] op_sel_hi:[1,0]
	v_pk_fma_f32 v[108:109], v[40:41], v[136:137], v[108:109]
	v_pk_fma_f32 v[110:111], v[42:43], v[138:139], v[110:111]
	global_store_dwordx4 v132, v[104:107], s[100:101] offset:128
	global_store_dwordx4 v132, v[108:111], s[100:101] offset:192
	s_add_u32 s100, s100, 0x20000
	s_addc_u32 s101, s101, 0
	v_pk_mul_f32 v[112:113], v[112:113], s[6:7] op_sel_hi:[1,0]
	v_pk_mul_f32 v[114:115], v[114:115], s[6:7] op_sel_hi:[1,0]
	v_pk_fma_f32 v[112:113], v[64:65], v[148:149], v[112:113]
	v_pk_fma_f32 v[114:115], v[66:67], v[150:151], v[114:115]
	v_pk_mul_f32 v[116:117], v[116:117], s[6:7] op_sel_hi:[1,0]
	v_pk_mul_f32 v[118:119], v[118:119], s[6:7] op_sel_hi:[1,0]
	v_pk_fma_f32 v[116:117], v[32:33], v[136:137], v[116:117]
	v_pk_fma_f32 v[118:119], v[34:35], v[138:139], v[118:119]
	global_store_dwordx4 v132, v[112:115], s[100:101] offset:128
	global_store_dwordx4 v132, v[116:119], s[100:101] offset:192
	s_add_u32 s100, s100, 0x20000
	s_addc_u32 s101, s101, 0
	v_pk_mul_f32 v[120:121], v[120:121], s[6:7] op_sel_hi:[1,0]
	v_pk_mul_f32 v[122:123], v[122:123], s[6:7] op_sel_hi:[1,0]
	v_pk_fma_f32 v[120:121], v[56:57], v[148:149], v[120:121]
	v_pk_fma_f32 v[122:123], v[58:59], v[150:151], v[122:123]
	v_pk_mul_f32 v[124:125], v[124:125], s[6:7] op_sel_hi:[1,0]
	v_pk_mul_f32 v[126:127], v[126:127], s[6:7] op_sel_hi:[1,0]
	v_pk_fma_f32 v[124:125], v[24:25], v[136:137], v[124:125]
	v_pk_fma_f32 v[126:127], v[26:27], v[138:139], v[126:127]
	global_store_dwordx4 v132, v[120:123], s[100:101] offset:128
	global_store_dwordx4 v132, v[124:127], s[100:101] offset:192
	s_add_u32 s100, s100, 0x20000
	s_addc_u32 s101, s101, 0
	v_pk_mul_f32 v[128:129], v[128:129], s[6:7] op_sel_hi:[1,0]
	v_pk_mul_f32 v[130:131], v[130:131], s[6:7] op_sel_hi:[1,0]
	v_pk_fma_f32 v[128:129], v[48:49], v[148:149], v[128:129]
	v_pk_fma_f32 v[130:131], v[50:51], v[150:151], v[130:131]
	v_pk_mul_f32 v[198:199], v[198:199], s[6:7] op_sel_hi:[1,0]
	v_pk_mul_f32 v[200:201], v[200:201], s[6:7] op_sel_hi:[1,0]
	v_pk_fma_f32 v[198:199], v[16:17], v[136:137], v[198:199]
	v_pk_fma_f32 v[200:201], v[18:19], v[138:139], v[200:201]
	global_store_dwordx4 v132, v[128:131], s[100:101] offset:128
	global_store_dwordx4 v132, v[198:201], s[100:101] offset:192
	s_add_u32 s100, s100, 0x20000
	s_addc_u32 s101, s101, 0
	v_pk_mul_f32 v[202:203], v[202:203], s[6:7] op_sel_hi:[1,0]
	v_pk_mul_f32 v[204:205], v[204:205], s[6:7] op_sel_hi:[1,0]
	v_pk_fma_f32 v[202:203], v[44:45], v[148:149], v[202:203]
	v_pk_fma_f32 v[204:205], v[46:47], v[150:151], v[204:205]
	v_pk_mul_f32 v[206:207], v[206:207], s[6:7] op_sel_hi:[1,0]
	v_pk_mul_f32 v[208:209], v[208:209], s[6:7] op_sel_hi:[1,0]
	v_pk_fma_f32 v[206:207], v[12:13], v[136:137], v[206:207]
	v_pk_fma_f32 v[208:209], v[14:15], v[138:139], v[208:209]
	global_store_dwordx4 v132, v[202:205], s[100:101] offset:128
	global_store_dwordx4 v132, v[206:209], s[100:101] offset:192
	s_add_u32 s100, s100, 0x20000
	s_addc_u32 s101, s101, 0
	v_pk_mul_f32 v[210:211], v[210:211], s[6:7] op_sel_hi:[1,0]
	v_pk_mul_f32 v[212:213], v[212:213], s[6:7] op_sel_hi:[1,0]
	v_pk_fma_f32 v[210:211], v[36:37], v[148:149], v[210:211]
	v_pk_fma_f32 v[212:213], v[38:39], v[150:151], v[212:213]
	v_pk_mul_f32 v[220:221], v[220:221], s[6:7] op_sel_hi:[1,0]
	v_pk_mul_f32 v[222:223], v[222:223], s[6:7] op_sel_hi:[1,0]
	v_pk_fma_f32 v[220:221], v[8:9], v[136:137], v[220:221]
	v_pk_fma_f32 v[222:223], v[10:11], v[138:139], v[222:223]
	global_store_dwordx4 v132, v[210:213], s[100:101] offset:128
	global_store_dwordx4 v132, v[220:223], s[100:101] offset:192
	s_add_u32 s100, s100, 0x20000
	s_addc_u32 s101, s101, 0
	v_pk_mul_f32 v[224:225], v[224:225], s[6:7] op_sel_hi:[1,0]
	v_pk_mul_f32 v[226:227], v[226:227], s[6:7] op_sel_hi:[1,0]
	v_pk_fma_f32 v[224:225], v[28:29], v[148:149], v[224:225]
	v_pk_fma_f32 v[226:227], v[30:31], v[150:151], v[226:227]
	v_pk_mul_f32 v[228:229], v[228:229], s[6:7] op_sel_hi:[1,0]
	v_pk_mul_f32 v[230:231], v[230:231], s[6:7] op_sel_hi:[1,0]
	v_pk_fma_f32 v[228:229], v[4:5], v[136:137], v[228:229]
	v_pk_fma_f32 v[230:231], v[6:7], v[138:139], v[230:231]
	global_store_dwordx4 v132, v[224:227], s[100:101] offset:128
	global_store_dwordx4 v132, v[228:231], s[100:101] offset:192
	s_add_u32 s100, s100, 0x20000
	s_addc_u32 s101, s101, 0
	v_pk_mul_f32 v[232:233], v[232:233], s[6:7] op_sel_hi:[1,0]
	v_pk_mul_f32 v[234:235], v[234:235], s[6:7] op_sel_hi:[1,0]
	v_pk_fma_f32 v[232:233], v[20:21], v[148:149], v[232:233]
	v_pk_fma_f32 v[234:235], v[22:23], v[150:151], v[234:235]
	v_pk_mul_f32 v[236:237], v[236:237], s[6:7] op_sel_hi:[1,0]
	v_pk_mul_f32 v[238:239], v[238:239], s[6:7] op_sel_hi:[1,0]
	v_pk_fma_f32 v[236:237], v[0:1], v[136:137], v[236:237]
	v_pk_fma_f32 v[238:239], v[2:3], v[138:139], v[238:239]
	global_store_dwordx4 v132, v[232:235], s[100:101] offset:128
	global_store_dwordx4 v132, v[236:239], s[100:101] offset:192
	s_add_i32 s20, s20, s3
	s_add_i32 s11, s11, s3
	v_readlane_b32 s66, v253, 18
	v_readlane_b32 s67, v253, 19
	v_readlane_b32 s68, v253, 20
	v_readlane_b32 s69, v253, 21
	v_readlane_b32 s70, v253, 22
	v_readlane_b32 s71, v253, 23
	v_readlane_b32 s72, v253, 24
	v_readlane_b32 s73, v253, 25
	v_readlane_b32 s74, v253, 26
	v_readlane_b32 s75, v253, 27
	v_readlane_b32 s76, v253, 28
	v_readlane_b32 s77, v253, 29
	v_readlane_b32 s78, v253, 30
	v_readlane_b32 s79, v253, 31
	s_cmpk_lt_u32 s20, 0x100
	s_cbranch_scc0 .LBB0_1035

; template <int PH>
; __global__ void __launch_bounds__(256, 2) mega(Params p) {
;   __shared__ __attribute__((aligned(16))) char smem[SMEM_BYTES];
	.amdhsa_kernel _Z4megaILin1EEv6Params
		.amdhsa_group_segment_fixed_size 73984
		.amdhsa_private_segment_fixed_size 0
		.amdhsa_kernarg_size 432
		.amdhsa_user_sgpr_count 2
		.amdhsa_user_sgpr_dispatch_ptr 0
		.amdhsa_user_sgpr_queue_ptr 0
		.amdhsa_user_sgpr_kernarg_segment_ptr 1
		.amdhsa_user_sgpr_dispatch_id 0
		.amdhsa_user_sgpr_kernarg_preload_length 0
		.amdhsa_user_sgpr_kernarg_preload_offset 0
		.amdhsa_user_sgpr_private_segment_size 0
		.amdhsa_uses_dynamic_stack 0
		.amdhsa_enable_private_segment 0
		.amdhsa_system_sgpr_workgroup_id_x 1
		.amdhsa_system_sgpr_workgroup_id_y 0
		.amdhsa_system_sgpr_workgroup_id_z 0
		.amdhsa_system_sgpr_workgroup_info 0
		.amdhsa_system_vgpr_workitem_id 2
		.amdhsa_next_free_vgpr 254
		.amdhsa_next_free_sgpr 102
		.amdhsa_accum_offset 256
		.amdhsa_reserve_vcc 1
		.amdhsa_float_round_mode_32 0
		.amdhsa_float_round_mode_16_64 0
		.amdhsa_float_denorm_mode_32 3
		.amdhsa_float_denorm_mode_16_64 3
		.amdhsa_dx10_clamp 1
		.amdhsa_ieee_mode 1
		.amdhsa_fp16_overflow 0
		.amdhsa_tg_split 0
		.amdhsa_exception_fp_ieee_invalid_op 0
		.amdhsa_exception_fp_denorm_src 0
		.amdhsa_exception_fp_ieee_div_zero 0
		.amdhsa_exception_fp_ieee_overflow 0
		.amdhsa_exception_fp_ieee_underflow 0
		.amdhsa_exception_fp_ieee_inexact 0
		.amdhsa_exception_int_div_zero 0
	.end_amdhsa_kernel

; template <int PH>
; __global__ void __launch_bounds__(256, 2) mega(Params p) {
;   __shared__ __attribute__((aligned(16))) char smem[SMEM_BYTES];
amdhsa.kernels:
  - .agpr_count:     0
    .args:
      - .offset:         0
        .size:           176
        .value_kind:     by_value
      - .offset:         176
        .size:           4
        .value_kind:     hidden_block_count_x
      - .offset:         180
        .size:           4
        .value_kind:     hidden_block_count_y
      - .offset:         184
        .size:           4
        .value_kind:     hidden_block_count_z
      - .offset:         188
        .size:           2
        .value_kind:     hidden_group_size_x
      - .offset:         190
        .size:           2
        .value_kind:     hidden_group_size_y
      - .offset:         192
        .size:           2
        .value_kind:     hidden_group_size_z
      - .offset:         194
        .size:           2
        .value_kind:     hidden_remainder_x
      - .offset:         196
        .size:           2
        .value_kind:     hidden_remainder_y
      - .offset:         198
        .size:           2
        .value_kind:     hidden_remainder_z
      - .offset:         216
        .size:           8
        .value_kind:     hidden_global_offset_x
      - .offset:         224
        .size:           8
        .value_kind:     hidden_global_offset_y
      - .offset:         232
        .size:           8
        .value_kind:     hidden_global_offset_z
      - .offset:         240
        .size:           2
        .value_kind:     hidden_grid_dims
      - .offset:         264
        .size:           8
        .value_kind:     hidden_multigrid_sync_arg
    .group_segment_fixed_size: 73984
    .kernarg_segment_align: 8
    .kernarg_segment_size: 432
    .language:       OpenCL C
    .language_version:
      - 2
      - 0
    .max_flat_workgroup_size: 256
    .name:           _Z4megaILin1EEv6Params
    .private_segment_fixed_size: 0
    .sgpr_count:     108
    .sgpr_spill_count: 87
    .symbol:         _Z4megaILin1EEv6Params.kd
    .uniform_work_group_size: 1
    .uses_dynamic_stack: false
    .vgpr_count:     254
    .vgpr_spill_count: 0
    .wavefront_size: 64
